# m_gates hand-written: weights held in VGPRs, all token rows loaded up front, pk fma, permlane/DPP butterfly, fill loads batched, bias loads hoisted
# speedup vs baseline: 1.0031x; 1.0031x over previous
; DI void phase_m_gates(int wv, const ArgP a, LAS unsigned char* lds) {
;     ...
;     for (int e = tid; e < 8192; e += 512) { const int k = e >> 3, j = e & 7; wgs[j * 1024 + k] = Wg[(size_t)k * 3080 + 3072 + j] * gn[k]; }
.LBB0_1370:
	s_mov_b64 s[0:1], s[82:83]
	s_load_dwordx2 s[2:3], s[0:1], 0xe8
	s_mov_b32 s4, s50
	v_mov_b32_e32 v9, v192
	s_nop 0
	v_lshl_add_u32 v0, s4, 6, v9
	s_movk_i32 s4, 0x2000
	v_cmp_gt_i32_e32 vcc, s4, v0
	v_and_b32_e32 v8, 7, v9
	s_and_saveexec_b64 s[4:5], vcc
	s_cbranch_execz .LBB0_1382
	s_load_dwordx4 s[8:11], s[0:1], 0x80
	v_lshrrev_b32_e32 v1, 3, v0
	v_lshlrev_b32_e32 v2, 2, v8
	s_movk_i32 s6, 0x3020
	v_lshlrev_b32_e32 v3, 2, v1
	v_mad_u32_u24 v2, v1, s6, v2
	v_lshl_add_u32 v10, v8, 12, v3
	s_waitcnt lgkmcnt(0)
	s_add_u32 s6, s10, 0x3000
	s_addc_u32 s7, s11, 0
	global_load_dword v48, v2, s[6:7]
	global_load_dword v64, v3, s[8:9]
	s_add_u32 s6, s6, 0xc0800
	s_addc_u32 s7, s7, 0
	global_load_dword v49, v2, s[6:7]
	global_load_dword v65, v3, s[8:9] offset:256
	s_add_u32 s6, s6, 0xc0800
	s_addc_u32 s7, s7, 0
	global_load_dword v50, v2, s[6:7]
	global_load_dword v66, v3, s[8:9] offset:512
	s_add_u32 s6, s6, 0xc0800
	s_addc_u32 s7, s7, 0
	global_load_dword v51, v2, s[6:7]
	global_load_dword v67, v3, s[8:9] offset:768
	s_add_u32 s6, s6, 0xc0800
	s_addc_u32 s7, s7, 0
	global_load_dword v52, v2, s[6:7]
	global_load_dword v68, v3, s[8:9] offset:1024
	s_add_u32 s6, s6, 0xc0800
	s_addc_u32 s7, s7, 0
	global_load_dword v53, v2, s[6:7]
	global_load_dword v69, v3, s[8:9] offset:1280
	s_add_u32 s6, s6, 0xc0800
	s_addc_u32 s7, s7, 0
	global_load_dword v54, v2, s[6:7]
	global_load_dword v70, v3, s[8:9] offset:1536
	s_add_u32 s6, s6, 0xc0800
	s_addc_u32 s7, s7, 0
	global_load_dword v55, v2, s[6:7]
	global_load_dword v71, v3, s[8:9] offset:1792
	s_add_u32 s6, s6, 0xc0800
	s_addc_u32 s7, s7, 0
	global_load_dword v56, v2, s[6:7]
	global_load_dword v72, v3, s[8:9] offset:2048
	s_add_u32 s6, s6, 0xc0800
	s_addc_u32 s7, s7, 0
	global_load_dword v57, v2, s[6:7]
	global_load_dword v73, v3, s[8:9] offset:2304
	s_add_u32 s6, s6, 0xc0800
	s_addc_u32 s7, s7, 0
	global_load_dword v58, v2, s[6:7]
	global_load_dword v74, v3, s[8:9] offset:2560
	s_add_u32 s6, s6, 0xc0800
	s_addc_u32 s7, s7, 0
	global_load_dword v59, v2, s[6:7]
	global_load_dword v75, v3, s[8:9] offset:2816
	s_add_u32 s6, s6, 0xc0800
	s_addc_u32 s7, s7, 0
	global_load_dword v60, v2, s[6:7]
	global_load_dword v76, v3, s[8:9] offset:3072
	s_add_u32 s6, s6, 0xc0800
	s_addc_u32 s7, s7, 0
	global_load_dword v61, v2, s[6:7]
	global_load_dword v77, v3, s[8:9] offset:3328
	s_add_u32 s6, s6, 0xc0800
	s_addc_u32 s7, s7, 0
	global_load_dword v62, v2, s[6:7]
	global_load_dword v78, v3, s[8:9] offset:3584
	s_add_u32 s6, s6, 0xc0800
	s_addc_u32 s7, s7, 0
	global_load_dword v63, v2, s[6:7]
	global_load_dword v79, v3, s[8:9] offset:3840
	s_add_u32 s6, s6, 0xc0800
	s_addc_u32 s7, s7, 0
	s_waitcnt vmcnt(30)
	v_mul_f32_e32 v48, v48, v64
	ds_write_b32 v10, v48
	s_waitcnt vmcnt(28)
	v_mul_f32_e32 v49, v49, v65
	ds_write_b32 v10, v49 offset:256
	s_waitcnt vmcnt(26)
	v_mul_f32_e32 v50, v50, v66
	ds_write_b32 v10, v50 offset:512
	s_waitcnt vmcnt(24)
	v_mul_f32_e32 v51, v51, v67
	ds_write_b32 v10, v51 offset:768
	s_waitcnt vmcnt(22)
	v_mul_f32_e32 v52, v52, v68
	ds_write_b32 v10, v52 offset:1024
	s_waitcnt vmcnt(20)
	v_mul_f32_e32 v53, v53, v69
	ds_write_b32 v10, v53 offset:1280
	s_waitcnt vmcnt(18)
	v_mul_f32_e32 v54, v54, v70
	ds_write_b32 v10, v54 offset:1536
	s_waitcnt vmcnt(16)
	v_mul_f32_e32 v55, v55, v71
	ds_write_b32 v10, v55 offset:1792
	s_waitcnt vmcnt(14)
	v_mul_f32_e32 v56, v56, v72
	ds_write_b32 v10, v56 offset:2048
	s_waitcnt vmcnt(12)
	v_mul_f32_e32 v57, v57, v73
	ds_write_b32 v10, v57 offset:2304
	s_waitcnt vmcnt(10)
	v_mul_f32_e32 v58, v58, v74
	ds_write_b32 v10, v58 offset:2560
	s_waitcnt vmcnt(8)
	v_mul_f32_e32 v59, v59, v75
	ds_write_b32 v10, v59 offset:2816
	s_waitcnt vmcnt(6)
	v_mul_f32_e32 v60, v60, v76
	ds_write_b32 v10, v60 offset:3072
	s_waitcnt vmcnt(4)
	v_mul_f32_e32 v61, v61, v77
	ds_write_b32 v10, v61 offset:3328
	s_waitcnt vmcnt(2)
	v_mul_f32_e32 v62, v62, v78
	ds_write_b32 v10, v62 offset:3584
	s_waitcnt vmcnt(0)
	v_mul_f32_e32 v63, v63, v79
	ds_write_b32 v10, v63 offset:3840

; #define LAS __attribute__((address_space(3)))
; DI float bflo(unsigned u) { return __uint_as_float(u << 16); }
; DI float bfhi(unsigned u) { return __uint_as_float(u & 0xffff0000u); }
; DI float rs_from_ss(u64 ssq) { return rsqrtf((float)ssq * (1.f / (1048576.f * 1024.f)) + EPS); }
; DI void phase_m_gates(int wv, const ArgP a, LAS unsigned char* lds) {
;     ...
;         for (int i = 0; i < 8; ++i) { const int t = c * 64 + wave * 8 + i;
;             float acc[8];
; #pragma unroll
;             for (int j = 0; j < 8; ++j) acc[j] = 0.f;
; #pragma unroll
;             for (int jj = 0; jj < 4; ++jj) { const int k0 = jj * 256 + lane * 4; const u32x2 hb = *(const u32x2*)(XBr + (size_t)t * 1024 + k0); const f32x4 hv = {bflo(hb.x), bfhi(hb.x), bflo(hb.y), bfhi(hb.y)};
; #pragma unroll
;                 for (int j = 0; j < 8; ++j) { const f32x4 wj = *(const LAS f32x4*)(wgs + j * 1024 + k0); acc[j] += hv[0] * wj[0] + hv[1] * wj[1] + hv[2] * wj[2] + hv[3] * wj[3]; } }
;             const float rs = rs_from_ss(rowss[t]);
.LBB0_1385:
	s_load_dwordx4 s[84:87], s[0:1], 0x90
	v_and_b32_e32 v25, 7, v192
	v_readfirstlane_b32 s46, v8
	v_add_lshl_u32 v25, v8, v25, 3
	s_add_u32 s72, s2, 0x1d88000
	s_addc_u32 s73, s3, 0
	global_load_dwordx2 v[242:243], v25, s[28:29]
	s_lshl_b32 s47, s46, 11
	s_add_u32 s72, s72, s47
	s_addc_u32 s73, s73, 0
	s_add_u32 s74, s72, 0x1000
	s_addc_u32 s75, s73, 0
	s_add_u32 s76, s72, 0x2000
	s_addc_u32 s77, s73, 0
	s_add_u32 s78, s72, 0x3000
	s_addc_u32 s79, s73, 0
	v_and_b32_e32 v9, 12, v12
	global_load_dwordx2 v[180:181], v4, s[72:73]
	global_load_dwordx2 v[182:183], v4, s[72:73] offset:512
	global_load_dwordx2 v[184:185], v4, s[72:73] offset:1024
	global_load_dwordx2 v[186:187], v4, s[72:73] offset:1536
	global_load_dwordx2 v[188:189], v4, s[72:73] offset:2048
	global_load_dwordx2 v[190:191], v4, s[72:73] offset:2560
	global_load_dwordx2 v[200:201], v4, s[72:73] offset:3072
	global_load_dwordx2 v[202:203], v4, s[72:73] offset:3584
	global_load_dwordx2 v[204:205], v4, s[74:75]
	global_load_dwordx2 v[206:207], v4, s[74:75] offset:512
	global_load_dwordx2 v[208:209], v4, s[74:75] offset:1024
	global_load_dwordx2 v[210:211], v4, s[74:75] offset:1536
	global_load_dwordx2 v[212:213], v4, s[74:75] offset:2048
	global_load_dwordx2 v[214:215], v4, s[74:75] offset:2560
	global_load_dwordx2 v[216:217], v4, s[74:75] offset:3072
	global_load_dwordx2 v[218:219], v4, s[74:75] offset:3584
	global_load_dwordx2 v[220:221], v4, s[76:77]
	global_load_dwordx2 v[222:223], v4, s[76:77] offset:512
	global_load_dwordx2 v[224:225], v4, s[76:77] offset:1024
	global_load_dwordx2 v[226:227], v4, s[76:77] offset:1536
	global_load_dwordx2 v[228:229], v4, s[76:77] offset:2048
	global_load_dwordx2 v[230:231], v4, s[76:77] offset:2560
	global_load_dwordx2 v[232:233], v4, s[76:77] offset:3072
	global_load_dwordx2 v[234:235], v4, s[76:77] offset:3584
	global_load_dwordx2 v[236:237], v4, s[78:79]
	global_load_dwordx2 v[238:239], v4, s[78:79] offset:512
	global_load_dwordx2 v[244:245], v4, s[78:79] offset:1024
	global_load_dwordx2 v[246:247], v4, s[78:79] offset:1536
	global_load_dwordx2 v[248:249], v4, s[78:79] offset:2048
	global_load_dwordx2 v[250:251], v4, s[78:79] offset:2560
	global_load_dwordx2 v[252:253], v4, s[78:79] offset:3072
	global_load_dwordx2 v[254:255], v4, s[78:79] offset:3584
	s_waitcnt lgkmcnt(0)
	global_load_dword v196, v9, s[84:85]
	global_load_dword v241, v9, s[86:87]
	ds_read_b128 v[48:51], v21
	ds_read_b128 v[52:55], v21 offset:4096
	ds_read_b128 v[56:59], v21 offset:8192
	ds_read_b128 v[60:63], v21 offset:12288
	ds_read_b128 v[64:67], v21 offset:16384
	ds_read_b128 v[68:71], v21 offset:20480
	ds_read_b128 v[72:75], v21 offset:24576
	ds_read_b128 v[76:79], v21 offset:28672
	ds_read_b128 v[80:83], v21 offset:1024
	ds_read_b128 v[84:87], v21 offset:5120
	ds_read_b128 v[88:91], v21 offset:9216
	ds_read_b128 v[92:95], v21 offset:13312
	ds_read_b128 v[96:99], v21 offset:17408
	ds_read_b128 v[100:103], v21 offset:21504
	ds_read_b128 v[104:107], v21 offset:25600
	ds_read_b128 v[108:111], v21 offset:29696
	ds_read_b128 v[112:115], v21 offset:2048
	ds_read_b128 v[116:119], v21 offset:6144
	ds_read_b128 v[120:123], v21 offset:10240
	ds_read_b128 v[124:127], v21 offset:14336
	ds_read_b128 v[128:131], v21 offset:18432
	ds_read_b128 v[132:135], v21 offset:22528
	ds_read_b128 v[140:143], v21 offset:26624
	ds_read_b128 v[144:147], v21 offset:30720
	ds_read_b128 v[148:151], v21 offset:3072
	ds_read_b128 v[152:155], v21 offset:7168
	ds_read_b128 v[156:159], v21 offset:11264
	ds_read_b128 v[160:163], v21 offset:15360
	ds_read_b128 v[164:167], v21 offset:19456
	ds_read_b128 v[168:171], v21 offset:23552
	ds_read_b128 v[172:175], v21 offset:27648
	ds_read_b128 v[176:179], v21 offset:31744
	s_waitcnt vmcnt(34)
	v_ffbh_u32_e32 v25, v243
	v_min_u32_e32 v25, 32, v25
	v_lshlrev_b64 v[242:243], v25, v[242:243]
	v_min_u32_e32 v242, 1, v242
	v_or_b32_e32 v242, v243, v242
	v_cvt_f32_u32_e32 v242, v242
	v_sub_u32_e32 v25, 32, v25
	v_ldexp_f32 v25, v242, v25
	v_fmamk_f32 v25, v25, 0x30800000, v22
	v_mul_f32_e32 v242, 0x4b800000, v25
	v_cmp_gt_f32_e32 vcc, s49, v25
	s_nop 1
	v_cndmask_b32_e32 v25, v25, v242, vcc
	v_rsq_f32_e32 v25, v25
	s_nop 0
	v_mul_f32_e32 v243, 0x45800000, v25
	v_cndmask_b32_e32 v138, v25, v243, vcc
	s_nop 1
	v_readlane_b32 s64, v138, 0
	v_readlane_b32 s65, v138, 1
	v_readlane_b32 s66, v138, 2
	v_readlane_b32 s67, v138, 3
	v_readlane_b32 s68, v138, 4
	v_readlane_b32 s69, v138, 5
	v_readlane_b32 s70, v138, 6
	v_readlane_b32 s71, v138, 7
	s_waitcnt lgkmcnt(0)
	s_waitcnt vmcnt(33)
	v_lshlrev_b32_e32 v14, 16, v180
	v_and_b32_e32 v15, 0xffff0000, v180
	v_lshlrev_b32_e32 v16, 16, v181
	v_and_b32_e32 v17, 0xffff0000, v181
	v_pk_mul_f32 v[26:27], v[14:15], v[48:49]
	v_pk_mul_f32 v[28:29], v[14:15], v[52:53]
	v_pk_mul_f32 v[30:31], v[14:15], v[56:57]
	v_pk_mul_f32 v[32:33], v[14:15], v[60:61]
	v_pk_mul_f32 v[34:35], v[14:15], v[64:65]
	v_pk_mul_f32 v[36:37], v[14:15], v[68:69]
	v_pk_mul_f32 v[38:39], v[14:15], v[72:73]
	v_pk_mul_f32 v[40:41], v[14:15], v[76:77]
	v_pk_fma_f32 v[26:27], v[16:17], v[50:51], v[26:27]
	v_pk_fma_f32 v[28:29], v[16:17], v[54:55], v[28:29]
	v_pk_fma_f32 v[30:31], v[16:17], v[58:59], v[30:31]
	v_pk_fma_f32 v[32:33], v[16:17], v[62:63], v[32:33]
	v_pk_fma_f32 v[34:35], v[16:17], v[66:67], v[34:35]
	v_pk_fma_f32 v[36:37], v[16:17], v[70:71], v[36:37]
	v_pk_fma_f32 v[38:39], v[16:17], v[74:75], v[38:39]
	v_pk_fma_f32 v[40:41], v[16:17], v[78:79], v[40:41]
	s_waitcnt vmcnt(32)
; #define LAS __attribute__((address_space(3)))
; DI float bflo(unsigned u) { return __uint_as_float(u << 16); }
; DI float bfhi(unsigned u) { return __uint_as_float(u & 0xffff0000u); }
; DI float rs_from_ss(u64 ssq) { return rsqrtf((float)ssq * (1.f / (1048576.f * 1024.f)) + EPS); }
; DI void phase_m_gates(int wv, const ArgP a, LAS unsigned char* lds) {
;     ...
;             for (int jj = 0; jj < 4; ++jj) { const int k0 = jj * 256 + lane * 4; const u32x2 hb = *(const u32x2*)(XBr + (size_t)t * 1024 + k0); const f32x4 hv = {bflo(hb.x), bfhi(hb.x), bflo(hb.y), bfhi(hb.y)};
; #pragma unroll
;                 for (int j = 0; j < 8; ++j) { const f32x4 wj = *(const LAS f32x4*)(wgs + j * 1024 + k0); acc[j] += hv[0] * wj[0] + hv[1] * wj[1] + hv[2] * wj[2] + hv[3] * wj[3]; } }
;             const float rs = rs_from_ss(rowss[t]);
;             { const bool b5 = lane & 32, b4 = lane & 16, b3 = lane & 8;
; #pragma unroll
;               for (int j = 0; j < 4; ++j) { const float snd = b5 ? acc[j] : acc[j + 4], kp = b5 ? acc[j + 4] : acc[j]; acc[j] = kp + __shfl_xor(snd, 32); }
; #pragma unroll
;               for (int j = 0; j < 2; ++j) { const float snd = b4 ? acc[j] : acc[j + 2], kp = b4 ? acc[j + 2] : acc[j]; acc[j] = kp + __shfl_xor(snd, 16); }
;               { const float snd = b3 ? acc[0] : acc[1], kp = b3 ? acc[1] : acc[0]; acc[0] = kp + __shfl_xor(snd, 8); }
;               acc[0] += __shfl_xor(acc[0], 4); acc[0] += __shfl_xor(acc[0], 2); acc[0] += __shfl_xor(acc[0], 1);
;               if ((lane & 7) == 0) pre[(wave * 8 + i) * 8 + (b5 ? 4 : 0) + (b4 ? 2 : 0) + (b3 ? 1 : 0)] = acc[0] * rs; }
	v_lshlrev_b32_e32 v18, 16, v182
	v_and_b32_e32 v19, 0xffff0000, v182
	v_lshlrev_b32_e32 v136, 16, v183
	v_and_b32_e32 v137, 0xffff0000, v183
	v_pk_fma_f32 v[26:27], v[18:19], v[80:81], v[26:27]
	v_pk_fma_f32 v[28:29], v[18:19], v[84:85], v[28:29]
	v_pk_fma_f32 v[30:31], v[18:19], v[88:89], v[30:31]
	v_pk_fma_f32 v[32:33], v[18:19], v[92:93], v[32:33]
	v_pk_fma_f32 v[34:35], v[18:19], v[96:97], v[34:35]
	v_pk_fma_f32 v[36:37], v[18:19], v[100:101], v[36:37]
	v_pk_fma_f32 v[38:39], v[18:19], v[104:105], v[38:39]
	v_pk_fma_f32 v[40:41], v[18:19], v[108:109], v[40:41]
	v_pk_fma_f32 v[26:27], v[136:137], v[82:83], v[26:27]
	v_pk_fma_f32 v[28:29], v[136:137], v[86:87], v[28:29]
	v_pk_fma_f32 v[30:31], v[136:137], v[90:91], v[30:31]
	v_pk_fma_f32 v[32:33], v[136:137], v[94:95], v[32:33]
	v_pk_fma_f32 v[34:35], v[136:137], v[98:99], v[34:35]
	v_pk_fma_f32 v[36:37], v[136:137], v[102:103], v[36:37]
	v_pk_fma_f32 v[38:39], v[136:137], v[106:107], v[38:39]
	v_pk_fma_f32 v[40:41], v[136:137], v[110:111], v[40:41]
	s_waitcnt vmcnt(31)
	v_lshlrev_b32_e32 v14, 16, v184
	v_and_b32_e32 v15, 0xffff0000, v184
	v_lshlrev_b32_e32 v16, 16, v185
	v_and_b32_e32 v17, 0xffff0000, v185
	v_pk_fma_f32 v[26:27], v[14:15], v[112:113], v[26:27]
	v_pk_fma_f32 v[28:29], v[14:15], v[116:117], v[28:29]
	v_pk_fma_f32 v[30:31], v[14:15], v[120:121], v[30:31]
	v_pk_fma_f32 v[32:33], v[14:15], v[124:125], v[32:33]
	v_pk_fma_f32 v[34:35], v[14:15], v[128:129], v[34:35]
	v_pk_fma_f32 v[36:37], v[14:15], v[132:133], v[36:37]
	v_pk_fma_f32 v[38:39], v[14:15], v[140:141], v[38:39]
	v_pk_fma_f32 v[40:41], v[14:15], v[144:145], v[40:41]
	v_pk_fma_f32 v[26:27], v[16:17], v[114:115], v[26:27]
	v_pk_fma_f32 v[28:29], v[16:17], v[118:119], v[28:29]
	v_pk_fma_f32 v[30:31], v[16:17], v[122:123], v[30:31]
	v_pk_fma_f32 v[32:33], v[16:17], v[126:127], v[32:33]
	v_pk_fma_f32 v[34:35], v[16:17], v[130:131], v[34:35]
	v_pk_fma_f32 v[36:37], v[16:17], v[134:135], v[36:37]
	v_pk_fma_f32 v[38:39], v[16:17], v[142:143], v[38:39]
	v_pk_fma_f32 v[40:41], v[16:17], v[146:147], v[40:41]
	s_waitcnt vmcnt(30)
	v_lshlrev_b32_e32 v18, 16, v186
	v_and_b32_e32 v19, 0xffff0000, v186
	v_lshlrev_b32_e32 v136, 16, v187
	v_and_b32_e32 v137, 0xffff0000, v187
	v_pk_fma_f32 v[26:27], v[18:19], v[148:149], v[26:27]
	v_pk_fma_f32 v[28:29], v[18:19], v[152:153], v[28:29]
	v_pk_fma_f32 v[30:31], v[18:19], v[156:157], v[30:31]
	v_pk_fma_f32 v[32:33], v[18:19], v[160:161], v[32:33]
	v_pk_fma_f32 v[34:35], v[18:19], v[164:165], v[34:35]
	v_pk_fma_f32 v[36:37], v[18:19], v[168:169], v[36:37]
	v_pk_fma_f32 v[38:39], v[18:19], v[172:173], v[38:39]
	v_pk_fma_f32 v[40:41], v[18:19], v[176:177], v[40:41]
	v_pk_fma_f32 v[26:27], v[136:137], v[150:151], v[26:27]
	v_pk_fma_f32 v[28:29], v[136:137], v[154:155], v[28:29]
	v_pk_fma_f32 v[30:31], v[136:137], v[158:159], v[30:31]
	v_pk_fma_f32 v[32:33], v[136:137], v[162:163], v[32:33]
	v_pk_fma_f32 v[34:35], v[136:137], v[166:167], v[34:35]
	v_pk_fma_f32 v[36:37], v[136:137], v[170:171], v[36:37]
	v_pk_fma_f32 v[38:39], v[136:137], v[174:175], v[38:39]
	v_pk_fma_f32 v[40:41], v[136:137], v[178:179], v[40:41]
	v_add_f32_e32 v26, v26, v27
	v_add_f32_e32 v28, v28, v29
	v_add_f32_e32 v30, v30, v31
	v_add_f32_e32 v32, v32, v33
	v_add_f32_e32 v34, v34, v35
	v_add_f32_e32 v36, v36, v37
	v_add_f32_e32 v38, v38, v39
	v_add_f32_e32 v40, v40, v41
	s_nop 1
	v_permlane32_swap_b32_e32 v26, v34
	v_permlane32_swap_b32_e32 v28, v36
	v_permlane32_swap_b32_e32 v30, v38
	v_permlane32_swap_b32_e32 v32, v40
	v_add_f32_e32 v26, v26, v34
	v_add_f32_e32 v30, v30, v38
	v_add_f32_e32 v28, v28, v36
	v_add_f32_e32 v32, v32, v40
	s_nop 1
	v_permlane16_swap_b32_e32 v26, v30
	v_permlane16_swap_b32_e32 v28, v32
	v_add_f32_e32 v26, v26, v30
	v_add_f32_e32 v28, v28, v32
	v_cndmask_b32_e64 v30, v26, v28, s[8:9]
	v_cndmask_b32_e64 v32, v28, v26, s[8:9]
	s_nop 1
	v_add_f32_dpp v26, v30, v32 row_ror:8 row_mask:0xf bank_mask:0xf
	s_nop 1
	v_add_f32_dpp v26, v26, v26 quad_perm:[1,0,3,2] row_mask:0xf bank_mask:0xf
	s_nop 1
	v_add_f32_dpp v26, v26, v26 quad_perm:[2,3,0,1] row_mask:0xf bank_mask:0xf
	s_nop 1
	v_add_f32_dpp v26, v26, v26 row_half_mirror row_mask:0xf bank_mask:0xf
	v_mul_f32_e32 v180, s64, v26
	s_waitcnt vmcnt(29)
	v_lshlrev_b32_e32 v14, 16, v188
	v_and_b32_e32 v15, 0xffff0000, v188
	v_lshlrev_b32_e32 v16, 16, v189
	v_and_b32_e32 v17, 0xffff0000, v189
	v_pk_mul_f32 v[26:27], v[14:15], v[48:49]
	v_pk_mul_f32 v[28:29], v[14:15], v[52:53]
	v_pk_mul_f32 v[30:31], v[14:15], v[56:57]
	v_pk_mul_f32 v[32:33], v[14:15], v[60:61]
	v_pk_mul_f32 v[34:35], v[14:15], v[64:65]
	v_pk_mul_f32 v[36:37], v[14:15], v[68:69]
	v_pk_mul_f32 v[38:39], v[14:15], v[72:73]
	v_pk_mul_f32 v[40:41], v[14:15], v[76:77]
	v_pk_fma_f32 v[26:27], v[16:17], v[50:51], v[26:27]
	v_pk_fma_f32 v[28:29], v[16:17], v[54:55], v[28:29]
	v_pk_fma_f32 v[30:31], v[16:17], v[58:59], v[30:31]
	v_pk_fma_f32 v[32:33], v[16:17], v[62:63], v[32:33]
	v_pk_fma_f32 v[34:35], v[16:17], v[66:67], v[34:35]
	v_pk_fma_f32 v[36:37], v[16:17], v[70:71], v[36:37]
	v_pk_fma_f32 v[38:39], v[16:17], v[74:75], v[38:39]
	v_pk_fma_f32 v[40:41], v[16:17], v[78:79], v[40:41]
	s_waitcnt vmcnt(28)
; #define LAS __attribute__((address_space(3)))
; DI float bflo(unsigned u) { return __uint_as_float(u << 16); }
; DI float bfhi(unsigned u) { return __uint_as_float(u & 0xffff0000u); }
; DI float rs_from_ss(u64 ssq) { return rsqrtf((float)ssq * (1.f / (1048576.f * 1024.f)) + EPS); }
; DI void phase_m_gates(int wv, const ArgP a, LAS unsigned char* lds) {
;     ...
;             for (int jj = 0; jj < 4; ++jj) { const int k0 = jj * 256 + lane * 4; const u32x2 hb = *(const u32x2*)(XBr + (size_t)t * 1024 + k0); const f32x4 hv = {bflo(hb.x), bfhi(hb.x), bflo(hb.y), bfhi(hb.y)};
; #pragma unroll
;                 for (int j = 0; j < 8; ++j) { const f32x4 wj = *(const LAS f32x4*)(wgs + j * 1024 + k0); acc[j] += hv[0] * wj[0] + hv[1] * wj[1] + hv[2] * wj[2] + hv[3] * wj[3]; } }
;             const float rs = rs_from_ss(rowss[t]);
;             { const bool b5 = lane & 32, b4 = lane & 16, b3 = lane & 8;
; #pragma unroll
;               for (int j = 0; j < 4; ++j) { const float snd = b5 ? acc[j] : acc[j + 4], kp = b5 ? acc[j + 4] : acc[j]; acc[j] = kp + __shfl_xor(snd, 32); }
; #pragma unroll
;               for (int j = 0; j < 2; ++j) { const float snd = b4 ? acc[j] : acc[j + 2], kp = b4 ? acc[j + 2] : acc[j]; acc[j] = kp + __shfl_xor(snd, 16); }
;               { const float snd = b3 ? acc[0] : acc[1], kp = b3 ? acc[1] : acc[0]; acc[0] = kp + __shfl_xor(snd, 8); }
;               acc[0] += __shfl_xor(acc[0], 4); acc[0] += __shfl_xor(acc[0], 2); acc[0] += __shfl_xor(acc[0], 1);
;               if ((lane & 7) == 0) pre[(wave * 8 + i) * 8 + (b5 ? 4 : 0) + (b4 ? 2 : 0) + (b3 ? 1 : 0)] = acc[0] * rs; }
	v_lshlrev_b32_e32 v18, 16, v190
	v_and_b32_e32 v19, 0xffff0000, v190
	v_lshlrev_b32_e32 v136, 16, v191
	v_and_b32_e32 v137, 0xffff0000, v191
	v_pk_fma_f32 v[26:27], v[18:19], v[80:81], v[26:27]
	v_pk_fma_f32 v[28:29], v[18:19], v[84:85], v[28:29]
	v_pk_fma_f32 v[30:31], v[18:19], v[88:89], v[30:31]
	v_pk_fma_f32 v[32:33], v[18:19], v[92:93], v[32:33]
	v_pk_fma_f32 v[34:35], v[18:19], v[96:97], v[34:35]
	v_pk_fma_f32 v[36:37], v[18:19], v[100:101], v[36:37]
	v_pk_fma_f32 v[38:39], v[18:19], v[104:105], v[38:39]
	v_pk_fma_f32 v[40:41], v[18:19], v[108:109], v[40:41]
	v_pk_fma_f32 v[26:27], v[136:137], v[82:83], v[26:27]
	v_pk_fma_f32 v[28:29], v[136:137], v[86:87], v[28:29]
	v_pk_fma_f32 v[30:31], v[136:137], v[90:91], v[30:31]
	v_pk_fma_f32 v[32:33], v[136:137], v[94:95], v[32:33]
	v_pk_fma_f32 v[34:35], v[136:137], v[98:99], v[34:35]
	v_pk_fma_f32 v[36:37], v[136:137], v[102:103], v[36:37]
	v_pk_fma_f32 v[38:39], v[136:137], v[106:107], v[38:39]
	v_pk_fma_f32 v[40:41], v[136:137], v[110:111], v[40:41]
	s_waitcnt vmcnt(27)
	v_lshlrev_b32_e32 v14, 16, v200
	v_and_b32_e32 v15, 0xffff0000, v200
	v_lshlrev_b32_e32 v16, 16, v201
	v_and_b32_e32 v17, 0xffff0000, v201
	v_pk_fma_f32 v[26:27], v[14:15], v[112:113], v[26:27]
	v_pk_fma_f32 v[28:29], v[14:15], v[116:117], v[28:29]
	v_pk_fma_f32 v[30:31], v[14:15], v[120:121], v[30:31]
	v_pk_fma_f32 v[32:33], v[14:15], v[124:125], v[32:33]
	v_pk_fma_f32 v[34:35], v[14:15], v[128:129], v[34:35]
	v_pk_fma_f32 v[36:37], v[14:15], v[132:133], v[36:37]
	v_pk_fma_f32 v[38:39], v[14:15], v[140:141], v[38:39]
	v_pk_fma_f32 v[40:41], v[14:15], v[144:145], v[40:41]
	v_pk_fma_f32 v[26:27], v[16:17], v[114:115], v[26:27]
	v_pk_fma_f32 v[28:29], v[16:17], v[118:119], v[28:29]
	v_pk_fma_f32 v[30:31], v[16:17], v[122:123], v[30:31]
	v_pk_fma_f32 v[32:33], v[16:17], v[126:127], v[32:33]
	v_pk_fma_f32 v[34:35], v[16:17], v[130:131], v[34:35]
	v_pk_fma_f32 v[36:37], v[16:17], v[134:135], v[36:37]
	v_pk_fma_f32 v[38:39], v[16:17], v[142:143], v[38:39]
	v_pk_fma_f32 v[40:41], v[16:17], v[146:147], v[40:41]
	s_waitcnt vmcnt(26)
	v_lshlrev_b32_e32 v18, 16, v202
	v_and_b32_e32 v19, 0xffff0000, v202
	v_lshlrev_b32_e32 v136, 16, v203
	v_and_b32_e32 v137, 0xffff0000, v203
	v_pk_fma_f32 v[26:27], v[18:19], v[148:149], v[26:27]
	v_pk_fma_f32 v[28:29], v[18:19], v[152:153], v[28:29]
	v_pk_fma_f32 v[30:31], v[18:19], v[156:157], v[30:31]
	v_pk_fma_f32 v[32:33], v[18:19], v[160:161], v[32:33]
	v_pk_fma_f32 v[34:35], v[18:19], v[164:165], v[34:35]
	v_pk_fma_f32 v[36:37], v[18:19], v[168:169], v[36:37]
	v_pk_fma_f32 v[38:39], v[18:19], v[172:173], v[38:39]
	v_pk_fma_f32 v[40:41], v[18:19], v[176:177], v[40:41]
	v_pk_fma_f32 v[26:27], v[136:137], v[150:151], v[26:27]
	v_pk_fma_f32 v[28:29], v[136:137], v[154:155], v[28:29]
	v_pk_fma_f32 v[30:31], v[136:137], v[158:159], v[30:31]
	v_pk_fma_f32 v[32:33], v[136:137], v[162:163], v[32:33]
	v_pk_fma_f32 v[34:35], v[136:137], v[166:167], v[34:35]
	v_pk_fma_f32 v[36:37], v[136:137], v[170:171], v[36:37]
	v_pk_fma_f32 v[38:39], v[136:137], v[174:175], v[38:39]
	v_pk_fma_f32 v[40:41], v[136:137], v[178:179], v[40:41]
	v_add_f32_e32 v26, v26, v27
	v_add_f32_e32 v28, v28, v29
	v_add_f32_e32 v30, v30, v31
	v_add_f32_e32 v32, v32, v33
	v_add_f32_e32 v34, v34, v35
	v_add_f32_e32 v36, v36, v37
	v_add_f32_e32 v38, v38, v39
	v_add_f32_e32 v40, v40, v41
	s_nop 1
	v_permlane32_swap_b32_e32 v26, v34
	v_permlane32_swap_b32_e32 v28, v36
	v_permlane32_swap_b32_e32 v30, v38
	v_permlane32_swap_b32_e32 v32, v40
	v_add_f32_e32 v26, v26, v34
	v_add_f32_e32 v30, v30, v38
	v_add_f32_e32 v28, v28, v36
	v_add_f32_e32 v32, v32, v40
	s_nop 1
	v_permlane16_swap_b32_e32 v26, v30
	v_permlane16_swap_b32_e32 v28, v32
	v_add_f32_e32 v26, v26, v30
	v_add_f32_e32 v28, v28, v32
	v_cndmask_b32_e64 v30, v26, v28, s[8:9]
	v_cndmask_b32_e64 v32, v28, v26, s[8:9]
	s_nop 1
	v_add_f32_dpp v26, v30, v32 row_ror:8 row_mask:0xf bank_mask:0xf
	s_nop 1
	v_add_f32_dpp v26, v26, v26 quad_perm:[1,0,3,2] row_mask:0xf bank_mask:0xf
	s_nop 1
	v_add_f32_dpp v26, v26, v26 quad_perm:[2,3,0,1] row_mask:0xf bank_mask:0xf
	s_nop 1
	v_add_f32_dpp v26, v26, v26 row_half_mirror row_mask:0xf bank_mask:0xf
	v_mul_f32_e32 v188, s65, v26
	s_waitcnt vmcnt(25)
	v_lshlrev_b32_e32 v14, 16, v204
	v_and_b32_e32 v15, 0xffff0000, v204
	v_lshlrev_b32_e32 v16, 16, v205
	v_and_b32_e32 v17, 0xffff0000, v205
	v_pk_mul_f32 v[26:27], v[14:15], v[48:49]
	v_pk_mul_f32 v[28:29], v[14:15], v[52:53]
	v_pk_mul_f32 v[30:31], v[14:15], v[56:57]
	v_pk_mul_f32 v[32:33], v[14:15], v[60:61]
	v_pk_mul_f32 v[34:35], v[14:15], v[64:65]
	v_pk_mul_f32 v[36:37], v[14:15], v[68:69]
	v_pk_mul_f32 v[38:39], v[14:15], v[72:73]
	v_pk_mul_f32 v[40:41], v[14:15], v[76:77]
	v_pk_fma_f32 v[26:27], v[16:17], v[50:51], v[26:27]
	v_pk_fma_f32 v[28:29], v[16:17], v[54:55], v[28:29]
	v_pk_fma_f32 v[30:31], v[16:17], v[58:59], v[30:31]
	v_pk_fma_f32 v[32:33], v[16:17], v[62:63], v[32:33]
	v_pk_fma_f32 v[34:35], v[16:17], v[66:67], v[34:35]
	v_pk_fma_f32 v[36:37], v[16:17], v[70:71], v[36:37]
	v_pk_fma_f32 v[38:39], v[16:17], v[74:75], v[38:39]
	v_pk_fma_f32 v[40:41], v[16:17], v[78:79], v[40:41]
	s_waitcnt vmcnt(24)
; #define LAS __attribute__((address_space(3)))
; DI float bflo(unsigned u) { return __uint_as_float(u << 16); }
; DI float bfhi(unsigned u) { return __uint_as_float(u & 0xffff0000u); }
; DI float rs_from_ss(u64 ssq) { return rsqrtf((float)ssq * (1.f / (1048576.f * 1024.f)) + EPS); }
; DI void phase_m_gates(int wv, const ArgP a, LAS unsigned char* lds) {
;     ...
;             for (int jj = 0; jj < 4; ++jj) { const int k0 = jj * 256 + lane * 4; const u32x2 hb = *(const u32x2*)(XBr + (size_t)t * 1024 + k0); const f32x4 hv = {bflo(hb.x), bfhi(hb.x), bflo(hb.y), bfhi(hb.y)};
; #pragma unroll
;                 for (int j = 0; j < 8; ++j) { const f32x4 wj = *(const LAS f32x4*)(wgs + j * 1024 + k0); acc[j] += hv[0] * wj[0] + hv[1] * wj[1] + hv[2] * wj[2] + hv[3] * wj[3]; } }
;             const float rs = rs_from_ss(rowss[t]);
;             { const bool b5 = lane & 32, b4 = lane & 16, b3 = lane & 8;
; #pragma unroll
;               for (int j = 0; j < 4; ++j) { const float snd = b5 ? acc[j] : acc[j + 4], kp = b5 ? acc[j + 4] : acc[j]; acc[j] = kp + __shfl_xor(snd, 32); }
; #pragma unroll
;               for (int j = 0; j < 2; ++j) { const float snd = b4 ? acc[j] : acc[j + 2], kp = b4 ? acc[j + 2] : acc[j]; acc[j] = kp + __shfl_xor(snd, 16); }
;               { const float snd = b3 ? acc[0] : acc[1], kp = b3 ? acc[1] : acc[0]; acc[0] = kp + __shfl_xor(snd, 8); }
;               acc[0] += __shfl_xor(acc[0], 4); acc[0] += __shfl_xor(acc[0], 2); acc[0] += __shfl_xor(acc[0], 1);
;               if ((lane & 7) == 0) pre[(wave * 8 + i) * 8 + (b5 ? 4 : 0) + (b4 ? 2 : 0) + (b3 ? 1 : 0)] = acc[0] * rs; }
	v_lshlrev_b32_e32 v18, 16, v206
	v_and_b32_e32 v19, 0xffff0000, v206
	v_lshlrev_b32_e32 v136, 16, v207
	v_and_b32_e32 v137, 0xffff0000, v207
	v_pk_fma_f32 v[26:27], v[18:19], v[80:81], v[26:27]
	v_pk_fma_f32 v[28:29], v[18:19], v[84:85], v[28:29]
	v_pk_fma_f32 v[30:31], v[18:19], v[88:89], v[30:31]
	v_pk_fma_f32 v[32:33], v[18:19], v[92:93], v[32:33]
	v_pk_fma_f32 v[34:35], v[18:19], v[96:97], v[34:35]
	v_pk_fma_f32 v[36:37], v[18:19], v[100:101], v[36:37]
	v_pk_fma_f32 v[38:39], v[18:19], v[104:105], v[38:39]
	v_pk_fma_f32 v[40:41], v[18:19], v[108:109], v[40:41]
	v_pk_fma_f32 v[26:27], v[136:137], v[82:83], v[26:27]
	v_pk_fma_f32 v[28:29], v[136:137], v[86:87], v[28:29]
	v_pk_fma_f32 v[30:31], v[136:137], v[90:91], v[30:31]
	v_pk_fma_f32 v[32:33], v[136:137], v[94:95], v[32:33]
	v_pk_fma_f32 v[34:35], v[136:137], v[98:99], v[34:35]
	v_pk_fma_f32 v[36:37], v[136:137], v[102:103], v[36:37]
	v_pk_fma_f32 v[38:39], v[136:137], v[106:107], v[38:39]
	v_pk_fma_f32 v[40:41], v[136:137], v[110:111], v[40:41]
	s_waitcnt vmcnt(23)
	v_lshlrev_b32_e32 v14, 16, v208
	v_and_b32_e32 v15, 0xffff0000, v208
	v_lshlrev_b32_e32 v16, 16, v209
	v_and_b32_e32 v17, 0xffff0000, v209
	v_pk_fma_f32 v[26:27], v[14:15], v[112:113], v[26:27]
	v_pk_fma_f32 v[28:29], v[14:15], v[116:117], v[28:29]
	v_pk_fma_f32 v[30:31], v[14:15], v[120:121], v[30:31]
	v_pk_fma_f32 v[32:33], v[14:15], v[124:125], v[32:33]
	v_pk_fma_f32 v[34:35], v[14:15], v[128:129], v[34:35]
	v_pk_fma_f32 v[36:37], v[14:15], v[132:133], v[36:37]
	v_pk_fma_f32 v[38:39], v[14:15], v[140:141], v[38:39]
	v_pk_fma_f32 v[40:41], v[14:15], v[144:145], v[40:41]
	v_pk_fma_f32 v[26:27], v[16:17], v[114:115], v[26:27]
	v_pk_fma_f32 v[28:29], v[16:17], v[118:119], v[28:29]
	v_pk_fma_f32 v[30:31], v[16:17], v[122:123], v[30:31]
	v_pk_fma_f32 v[32:33], v[16:17], v[126:127], v[32:33]
	v_pk_fma_f32 v[34:35], v[16:17], v[130:131], v[34:35]
	v_pk_fma_f32 v[36:37], v[16:17], v[134:135], v[36:37]
	v_pk_fma_f32 v[38:39], v[16:17], v[142:143], v[38:39]
	v_pk_fma_f32 v[40:41], v[16:17], v[146:147], v[40:41]
	s_waitcnt vmcnt(22)
	v_lshlrev_b32_e32 v18, 16, v210
	v_and_b32_e32 v19, 0xffff0000, v210
	v_lshlrev_b32_e32 v136, 16, v211
	v_and_b32_e32 v137, 0xffff0000, v211
	v_pk_fma_f32 v[26:27], v[18:19], v[148:149], v[26:27]
	v_pk_fma_f32 v[28:29], v[18:19], v[152:153], v[28:29]
	v_pk_fma_f32 v[30:31], v[18:19], v[156:157], v[30:31]
	v_pk_fma_f32 v[32:33], v[18:19], v[160:161], v[32:33]
	v_pk_fma_f32 v[34:35], v[18:19], v[164:165], v[34:35]
	v_pk_fma_f32 v[36:37], v[18:19], v[168:169], v[36:37]
	v_pk_fma_f32 v[38:39], v[18:19], v[172:173], v[38:39]
	v_pk_fma_f32 v[40:41], v[18:19], v[176:177], v[40:41]
	v_pk_fma_f32 v[26:27], v[136:137], v[150:151], v[26:27]
	v_pk_fma_f32 v[28:29], v[136:137], v[154:155], v[28:29]
	v_pk_fma_f32 v[30:31], v[136:137], v[158:159], v[30:31]
	v_pk_fma_f32 v[32:33], v[136:137], v[162:163], v[32:33]
	v_pk_fma_f32 v[34:35], v[136:137], v[166:167], v[34:35]
	v_pk_fma_f32 v[36:37], v[136:137], v[170:171], v[36:37]
	v_pk_fma_f32 v[38:39], v[136:137], v[174:175], v[38:39]
	v_pk_fma_f32 v[40:41], v[136:137], v[178:179], v[40:41]
	v_add_f32_e32 v26, v26, v27
	v_add_f32_e32 v28, v28, v29
	v_add_f32_e32 v30, v30, v31
	v_add_f32_e32 v32, v32, v33
	v_add_f32_e32 v34, v34, v35
	v_add_f32_e32 v36, v36, v37
	v_add_f32_e32 v38, v38, v39
	v_add_f32_e32 v40, v40, v41
	s_nop 1
	v_permlane32_swap_b32_e32 v26, v34
	v_permlane32_swap_b32_e32 v28, v36
	v_permlane32_swap_b32_e32 v30, v38
	v_permlane32_swap_b32_e32 v32, v40
	v_add_f32_e32 v26, v26, v34
	v_add_f32_e32 v30, v30, v38
	v_add_f32_e32 v28, v28, v36
	v_add_f32_e32 v32, v32, v40
	s_nop 1
	v_permlane16_swap_b32_e32 v26, v30
	v_permlane16_swap_b32_e32 v28, v32
	v_add_f32_e32 v26, v26, v30
	v_add_f32_e32 v28, v28, v32
	v_cndmask_b32_e64 v30, v26, v28, s[8:9]
	v_cndmask_b32_e64 v32, v28, v26, s[8:9]
	s_nop 1
	v_add_f32_dpp v26, v30, v32 row_ror:8 row_mask:0xf bank_mask:0xf
	s_nop 1
	v_add_f32_dpp v26, v26, v26 quad_perm:[1,0,3,2] row_mask:0xf bank_mask:0xf
	s_nop 1
	v_add_f32_dpp v26, v26, v26 quad_perm:[2,3,0,1] row_mask:0xf bank_mask:0xf
	s_nop 1
	v_add_f32_dpp v26, v26, v26 row_half_mirror row_mask:0xf bank_mask:0xf
	v_mul_f32_e32 v204, s66, v26
	s_waitcnt vmcnt(21)
	v_lshlrev_b32_e32 v14, 16, v212
	v_and_b32_e32 v15, 0xffff0000, v212
	v_lshlrev_b32_e32 v16, 16, v213
	v_and_b32_e32 v17, 0xffff0000, v213
	v_pk_mul_f32 v[26:27], v[14:15], v[48:49]
	v_pk_mul_f32 v[28:29], v[14:15], v[52:53]
	v_pk_mul_f32 v[30:31], v[14:15], v[56:57]
	v_pk_mul_f32 v[32:33], v[14:15], v[60:61]
	v_pk_mul_f32 v[34:35], v[14:15], v[64:65]
	v_pk_mul_f32 v[36:37], v[14:15], v[68:69]
	v_pk_mul_f32 v[38:39], v[14:15], v[72:73]
	v_pk_mul_f32 v[40:41], v[14:15], v[76:77]
	v_pk_fma_f32 v[26:27], v[16:17], v[50:51], v[26:27]
	v_pk_fma_f32 v[28:29], v[16:17], v[54:55], v[28:29]
	v_pk_fma_f32 v[30:31], v[16:17], v[58:59], v[30:31]
	v_pk_fma_f32 v[32:33], v[16:17], v[62:63], v[32:33]
	v_pk_fma_f32 v[34:35], v[16:17], v[66:67], v[34:35]
	v_pk_fma_f32 v[36:37], v[16:17], v[70:71], v[36:37]
	v_pk_fma_f32 v[38:39], v[16:17], v[74:75], v[38:39]
	v_pk_fma_f32 v[40:41], v[16:17], v[78:79], v[40:41]
	s_waitcnt vmcnt(20)
; #define LAS __attribute__((address_space(3)))
; DI float bflo(unsigned u) { return __uint_as_float(u << 16); }
; DI float bfhi(unsigned u) { return __uint_as_float(u & 0xffff0000u); }
; DI float rs_from_ss(u64 ssq) { return rsqrtf((float)ssq * (1.f / (1048576.f * 1024.f)) + EPS); }
; DI void phase_m_gates(int wv, const ArgP a, LAS unsigned char* lds) {
;     ...
;             for (int jj = 0; jj < 4; ++jj) { const int k0 = jj * 256 + lane * 4; const u32x2 hb = *(const u32x2*)(XBr + (size_t)t * 1024 + k0); const f32x4 hv = {bflo(hb.x), bfhi(hb.x), bflo(hb.y), bfhi(hb.y)};
; #pragma unroll
;                 for (int j = 0; j < 8; ++j) { const f32x4 wj = *(const LAS f32x4*)(wgs + j * 1024 + k0); acc[j] += hv[0] * wj[0] + hv[1] * wj[1] + hv[2] * wj[2] + hv[3] * wj[3]; } }
;             const float rs = rs_from_ss(rowss[t]);
;             { const bool b5 = lane & 32, b4 = lane & 16, b3 = lane & 8;
; #pragma unroll
;               for (int j = 0; j < 4; ++j) { const float snd = b5 ? acc[j] : acc[j + 4], kp = b5 ? acc[j + 4] : acc[j]; acc[j] = kp + __shfl_xor(snd, 32); }
; #pragma unroll
;               for (int j = 0; j < 2; ++j) { const float snd = b4 ? acc[j] : acc[j + 2], kp = b4 ? acc[j + 2] : acc[j]; acc[j] = kp + __shfl_xor(snd, 16); }
;               { const float snd = b3 ? acc[0] : acc[1], kp = b3 ? acc[1] : acc[0]; acc[0] = kp + __shfl_xor(snd, 8); }
;               acc[0] += __shfl_xor(acc[0], 4); acc[0] += __shfl_xor(acc[0], 2); acc[0] += __shfl_xor(acc[0], 1);
;               if ((lane & 7) == 0) pre[(wave * 8 + i) * 8 + (b5 ? 4 : 0) + (b4 ? 2 : 0) + (b3 ? 1 : 0)] = acc[0] * rs; }
	v_lshlrev_b32_e32 v18, 16, v214
	v_and_b32_e32 v19, 0xffff0000, v214
	v_lshlrev_b32_e32 v136, 16, v215
	v_and_b32_e32 v137, 0xffff0000, v215
	v_pk_fma_f32 v[26:27], v[18:19], v[80:81], v[26:27]
	v_pk_fma_f32 v[28:29], v[18:19], v[84:85], v[28:29]
	v_pk_fma_f32 v[30:31], v[18:19], v[88:89], v[30:31]
	v_pk_fma_f32 v[32:33], v[18:19], v[92:93], v[32:33]
	v_pk_fma_f32 v[34:35], v[18:19], v[96:97], v[34:35]
	v_pk_fma_f32 v[36:37], v[18:19], v[100:101], v[36:37]
	v_pk_fma_f32 v[38:39], v[18:19], v[104:105], v[38:39]
	v_pk_fma_f32 v[40:41], v[18:19], v[108:109], v[40:41]
	v_pk_fma_f32 v[26:27], v[136:137], v[82:83], v[26:27]
	v_pk_fma_f32 v[28:29], v[136:137], v[86:87], v[28:29]
	v_pk_fma_f32 v[30:31], v[136:137], v[90:91], v[30:31]
	v_pk_fma_f32 v[32:33], v[136:137], v[94:95], v[32:33]
	v_pk_fma_f32 v[34:35], v[136:137], v[98:99], v[34:35]
	v_pk_fma_f32 v[36:37], v[136:137], v[102:103], v[36:37]
	v_pk_fma_f32 v[38:39], v[136:137], v[106:107], v[38:39]
	v_pk_fma_f32 v[40:41], v[136:137], v[110:111], v[40:41]
	s_waitcnt vmcnt(19)
	v_lshlrev_b32_e32 v14, 16, v216
	v_and_b32_e32 v15, 0xffff0000, v216
	v_lshlrev_b32_e32 v16, 16, v217
	v_and_b32_e32 v17, 0xffff0000, v217
	v_pk_fma_f32 v[26:27], v[14:15], v[112:113], v[26:27]
	v_pk_fma_f32 v[28:29], v[14:15], v[116:117], v[28:29]
	v_pk_fma_f32 v[30:31], v[14:15], v[120:121], v[30:31]
	v_pk_fma_f32 v[32:33], v[14:15], v[124:125], v[32:33]
	v_pk_fma_f32 v[34:35], v[14:15], v[128:129], v[34:35]
	v_pk_fma_f32 v[36:37], v[14:15], v[132:133], v[36:37]
	v_pk_fma_f32 v[38:39], v[14:15], v[140:141], v[38:39]
	v_pk_fma_f32 v[40:41], v[14:15], v[144:145], v[40:41]
	v_pk_fma_f32 v[26:27], v[16:17], v[114:115], v[26:27]
	v_pk_fma_f32 v[28:29], v[16:17], v[118:119], v[28:29]
	v_pk_fma_f32 v[30:31], v[16:17], v[122:123], v[30:31]
	v_pk_fma_f32 v[32:33], v[16:17], v[126:127], v[32:33]
	v_pk_fma_f32 v[34:35], v[16:17], v[130:131], v[34:35]
	v_pk_fma_f32 v[36:37], v[16:17], v[134:135], v[36:37]
	v_pk_fma_f32 v[38:39], v[16:17], v[142:143], v[38:39]
	v_pk_fma_f32 v[40:41], v[16:17], v[146:147], v[40:41]
	s_waitcnt vmcnt(18)
	v_lshlrev_b32_e32 v18, 16, v218
	v_and_b32_e32 v19, 0xffff0000, v218
	v_lshlrev_b32_e32 v136, 16, v219
	v_and_b32_e32 v137, 0xffff0000, v219
	v_pk_fma_f32 v[26:27], v[18:19], v[148:149], v[26:27]
	v_pk_fma_f32 v[28:29], v[18:19], v[152:153], v[28:29]
	v_pk_fma_f32 v[30:31], v[18:19], v[156:157], v[30:31]
	v_pk_fma_f32 v[32:33], v[18:19], v[160:161], v[32:33]
	v_pk_fma_f32 v[34:35], v[18:19], v[164:165], v[34:35]
	v_pk_fma_f32 v[36:37], v[18:19], v[168:169], v[36:37]
	v_pk_fma_f32 v[38:39], v[18:19], v[172:173], v[38:39]
	v_pk_fma_f32 v[40:41], v[18:19], v[176:177], v[40:41]
	v_pk_fma_f32 v[26:27], v[136:137], v[150:151], v[26:27]
	v_pk_fma_f32 v[28:29], v[136:137], v[154:155], v[28:29]
	v_pk_fma_f32 v[30:31], v[136:137], v[158:159], v[30:31]
	v_pk_fma_f32 v[32:33], v[136:137], v[162:163], v[32:33]
	v_pk_fma_f32 v[34:35], v[136:137], v[166:167], v[34:35]
	v_pk_fma_f32 v[36:37], v[136:137], v[170:171], v[36:37]
	v_pk_fma_f32 v[38:39], v[136:137], v[174:175], v[38:39]
	v_pk_fma_f32 v[40:41], v[136:137], v[178:179], v[40:41]
	v_add_f32_e32 v26, v26, v27
	v_add_f32_e32 v28, v28, v29
	v_add_f32_e32 v30, v30, v31
	v_add_f32_e32 v32, v32, v33
	v_add_f32_e32 v34, v34, v35
	v_add_f32_e32 v36, v36, v37
	v_add_f32_e32 v38, v38, v39
	v_add_f32_e32 v40, v40, v41
	s_nop 1
	v_permlane32_swap_b32_e32 v26, v34
	v_permlane32_swap_b32_e32 v28, v36
	v_permlane32_swap_b32_e32 v30, v38
	v_permlane32_swap_b32_e32 v32, v40
	v_add_f32_e32 v26, v26, v34
	v_add_f32_e32 v30, v30, v38
	v_add_f32_e32 v28, v28, v36
	v_add_f32_e32 v32, v32, v40
	s_nop 1
	v_permlane16_swap_b32_e32 v26, v30
	v_permlane16_swap_b32_e32 v28, v32
	v_add_f32_e32 v26, v26, v30
	v_add_f32_e32 v28, v28, v32
	v_cndmask_b32_e64 v30, v26, v28, s[8:9]
	v_cndmask_b32_e64 v32, v28, v26, s[8:9]
	s_nop 1
	v_add_f32_dpp v26, v30, v32 row_ror:8 row_mask:0xf bank_mask:0xf
	s_nop 1
	v_add_f32_dpp v26, v26, v26 quad_perm:[1,0,3,2] row_mask:0xf bank_mask:0xf
	s_nop 1
	v_add_f32_dpp v26, v26, v26 quad_perm:[2,3,0,1] row_mask:0xf bank_mask:0xf
	s_nop 1
	v_add_f32_dpp v26, v26, v26 row_half_mirror row_mask:0xf bank_mask:0xf
	v_mul_f32_e32 v212, s67, v26
	s_waitcnt vmcnt(17)
	v_lshlrev_b32_e32 v14, 16, v220
	v_and_b32_e32 v15, 0xffff0000, v220
	v_lshlrev_b32_e32 v16, 16, v221
	v_and_b32_e32 v17, 0xffff0000, v221
	v_pk_mul_f32 v[26:27], v[14:15], v[48:49]
	v_pk_mul_f32 v[28:29], v[14:15], v[52:53]
	v_pk_mul_f32 v[30:31], v[14:15], v[56:57]
	v_pk_mul_f32 v[32:33], v[14:15], v[60:61]
	v_pk_mul_f32 v[34:35], v[14:15], v[64:65]
	v_pk_mul_f32 v[36:37], v[14:15], v[68:69]
	v_pk_mul_f32 v[38:39], v[14:15], v[72:73]
	v_pk_mul_f32 v[40:41], v[14:15], v[76:77]
	v_pk_fma_f32 v[26:27], v[16:17], v[50:51], v[26:27]
	v_pk_fma_f32 v[28:29], v[16:17], v[54:55], v[28:29]
	v_pk_fma_f32 v[30:31], v[16:17], v[58:59], v[30:31]
	v_pk_fma_f32 v[32:33], v[16:17], v[62:63], v[32:33]
	v_pk_fma_f32 v[34:35], v[16:17], v[66:67], v[34:35]
	v_pk_fma_f32 v[36:37], v[16:17], v[70:71], v[36:37]
	v_pk_fma_f32 v[38:39], v[16:17], v[74:75], v[38:39]
	v_pk_fma_f32 v[40:41], v[16:17], v[78:79], v[40:41]
	s_waitcnt vmcnt(16)
; #define LAS __attribute__((address_space(3)))
; DI float bflo(unsigned u) { return __uint_as_float(u << 16); }
; DI float bfhi(unsigned u) { return __uint_as_float(u & 0xffff0000u); }
; DI float rs_from_ss(u64 ssq) { return rsqrtf((float)ssq * (1.f / (1048576.f * 1024.f)) + EPS); }
; DI void phase_m_gates(int wv, const ArgP a, LAS unsigned char* lds) {
;     ...
;             for (int jj = 0; jj < 4; ++jj) { const int k0 = jj * 256 + lane * 4; const u32x2 hb = *(const u32x2*)(XBr + (size_t)t * 1024 + k0); const f32x4 hv = {bflo(hb.x), bfhi(hb.x), bflo(hb.y), bfhi(hb.y)};
; #pragma unroll
;                 for (int j = 0; j < 8; ++j) { const f32x4 wj = *(const LAS f32x4*)(wgs + j * 1024 + k0); acc[j] += hv[0] * wj[0] + hv[1] * wj[1] + hv[2] * wj[2] + hv[3] * wj[3]; } }
;             const float rs = rs_from_ss(rowss[t]);
;             { const bool b5 = lane & 32, b4 = lane & 16, b3 = lane & 8;
; #pragma unroll
;               for (int j = 0; j < 4; ++j) { const float snd = b5 ? acc[j] : acc[j + 4], kp = b5 ? acc[j + 4] : acc[j]; acc[j] = kp + __shfl_xor(snd, 32); }
; #pragma unroll
;               for (int j = 0; j < 2; ++j) { const float snd = b4 ? acc[j] : acc[j + 2], kp = b4 ? acc[j + 2] : acc[j]; acc[j] = kp + __shfl_xor(snd, 16); }
;               { const float snd = b3 ? acc[0] : acc[1], kp = b3 ? acc[1] : acc[0]; acc[0] = kp + __shfl_xor(snd, 8); }
;               acc[0] += __shfl_xor(acc[0], 4); acc[0] += __shfl_xor(acc[0], 2); acc[0] += __shfl_xor(acc[0], 1);
;               if ((lane & 7) == 0) pre[(wave * 8 + i) * 8 + (b5 ? 4 : 0) + (b4 ? 2 : 0) + (b3 ? 1 : 0)] = acc[0] * rs; }
	v_lshlrev_b32_e32 v18, 16, v222
	v_and_b32_e32 v19, 0xffff0000, v222
	v_lshlrev_b32_e32 v136, 16, v223
	v_and_b32_e32 v137, 0xffff0000, v223
	v_pk_fma_f32 v[26:27], v[18:19], v[80:81], v[26:27]
	v_pk_fma_f32 v[28:29], v[18:19], v[84:85], v[28:29]
	v_pk_fma_f32 v[30:31], v[18:19], v[88:89], v[30:31]
	v_pk_fma_f32 v[32:33], v[18:19], v[92:93], v[32:33]
	v_pk_fma_f32 v[34:35], v[18:19], v[96:97], v[34:35]
	v_pk_fma_f32 v[36:37], v[18:19], v[100:101], v[36:37]
	v_pk_fma_f32 v[38:39], v[18:19], v[104:105], v[38:39]
	v_pk_fma_f32 v[40:41], v[18:19], v[108:109], v[40:41]
	v_pk_fma_f32 v[26:27], v[136:137], v[82:83], v[26:27]
	v_pk_fma_f32 v[28:29], v[136:137], v[86:87], v[28:29]
	v_pk_fma_f32 v[30:31], v[136:137], v[90:91], v[30:31]
	v_pk_fma_f32 v[32:33], v[136:137], v[94:95], v[32:33]
	v_pk_fma_f32 v[34:35], v[136:137], v[98:99], v[34:35]
	v_pk_fma_f32 v[36:37], v[136:137], v[102:103], v[36:37]
	v_pk_fma_f32 v[38:39], v[136:137], v[106:107], v[38:39]
	v_pk_fma_f32 v[40:41], v[136:137], v[110:111], v[40:41]
	s_waitcnt vmcnt(15)
	v_lshlrev_b32_e32 v14, 16, v224
	v_and_b32_e32 v15, 0xffff0000, v224
	v_lshlrev_b32_e32 v16, 16, v225
	v_and_b32_e32 v17, 0xffff0000, v225
	v_pk_fma_f32 v[26:27], v[14:15], v[112:113], v[26:27]
	v_pk_fma_f32 v[28:29], v[14:15], v[116:117], v[28:29]
	v_pk_fma_f32 v[30:31], v[14:15], v[120:121], v[30:31]
	v_pk_fma_f32 v[32:33], v[14:15], v[124:125], v[32:33]
	v_pk_fma_f32 v[34:35], v[14:15], v[128:129], v[34:35]
	v_pk_fma_f32 v[36:37], v[14:15], v[132:133], v[36:37]
	v_pk_fma_f32 v[38:39], v[14:15], v[140:141], v[38:39]
	v_pk_fma_f32 v[40:41], v[14:15], v[144:145], v[40:41]
	v_pk_fma_f32 v[26:27], v[16:17], v[114:115], v[26:27]
	v_pk_fma_f32 v[28:29], v[16:17], v[118:119], v[28:29]
	v_pk_fma_f32 v[30:31], v[16:17], v[122:123], v[30:31]
	v_pk_fma_f32 v[32:33], v[16:17], v[126:127], v[32:33]
	v_pk_fma_f32 v[34:35], v[16:17], v[130:131], v[34:35]
	v_pk_fma_f32 v[36:37], v[16:17], v[134:135], v[36:37]
	v_pk_fma_f32 v[38:39], v[16:17], v[142:143], v[38:39]
	v_pk_fma_f32 v[40:41], v[16:17], v[146:147], v[40:41]
	s_waitcnt vmcnt(14)
	v_lshlrev_b32_e32 v18, 16, v226
	v_and_b32_e32 v19, 0xffff0000, v226
	v_lshlrev_b32_e32 v136, 16, v227
	v_and_b32_e32 v137, 0xffff0000, v227
	v_pk_fma_f32 v[26:27], v[18:19], v[148:149], v[26:27]
	v_pk_fma_f32 v[28:29], v[18:19], v[152:153], v[28:29]
	v_pk_fma_f32 v[30:31], v[18:19], v[156:157], v[30:31]
	v_pk_fma_f32 v[32:33], v[18:19], v[160:161], v[32:33]
	v_pk_fma_f32 v[34:35], v[18:19], v[164:165], v[34:35]
	v_pk_fma_f32 v[36:37], v[18:19], v[168:169], v[36:37]
	v_pk_fma_f32 v[38:39], v[18:19], v[172:173], v[38:39]
	v_pk_fma_f32 v[40:41], v[18:19], v[176:177], v[40:41]
	v_pk_fma_f32 v[26:27], v[136:137], v[150:151], v[26:27]
	v_pk_fma_f32 v[28:29], v[136:137], v[154:155], v[28:29]
	v_pk_fma_f32 v[30:31], v[136:137], v[158:159], v[30:31]
	v_pk_fma_f32 v[32:33], v[136:137], v[162:163], v[32:33]
	v_pk_fma_f32 v[34:35], v[136:137], v[166:167], v[34:35]
	v_pk_fma_f32 v[36:37], v[136:137], v[170:171], v[36:37]
	v_pk_fma_f32 v[38:39], v[136:137], v[174:175], v[38:39]
	v_pk_fma_f32 v[40:41], v[136:137], v[178:179], v[40:41]
	v_add_f32_e32 v26, v26, v27
	v_add_f32_e32 v28, v28, v29
	v_add_f32_e32 v30, v30, v31
	v_add_f32_e32 v32, v32, v33
	v_add_f32_e32 v34, v34, v35
	v_add_f32_e32 v36, v36, v37
	v_add_f32_e32 v38, v38, v39
	v_add_f32_e32 v40, v40, v41
	s_nop 1
	v_permlane32_swap_b32_e32 v26, v34
	v_permlane32_swap_b32_e32 v28, v36
	v_permlane32_swap_b32_e32 v30, v38
	v_permlane32_swap_b32_e32 v32, v40
	v_add_f32_e32 v26, v26, v34
	v_add_f32_e32 v30, v30, v38
	v_add_f32_e32 v28, v28, v36
	v_add_f32_e32 v32, v32, v40
	s_nop 1
	v_permlane16_swap_b32_e32 v26, v30
	v_permlane16_swap_b32_e32 v28, v32
	v_add_f32_e32 v26, v26, v30
	v_add_f32_e32 v28, v28, v32
	v_cndmask_b32_e64 v30, v26, v28, s[8:9]
	v_cndmask_b32_e64 v32, v28, v26, s[8:9]
	s_nop 1
	v_add_f32_dpp v26, v30, v32 row_ror:8 row_mask:0xf bank_mask:0xf
	s_nop 1
	v_add_f32_dpp v26, v26, v26 quad_perm:[1,0,3,2] row_mask:0xf bank_mask:0xf
	s_nop 1
	v_add_f32_dpp v26, v26, v26 quad_perm:[2,3,0,1] row_mask:0xf bank_mask:0xf
	s_nop 1
	v_add_f32_dpp v26, v26, v26 row_half_mirror row_mask:0xf bank_mask:0xf
	v_mul_f32_e32 v220, s68, v26
	s_waitcnt vmcnt(13)
	v_lshlrev_b32_e32 v14, 16, v228
	v_and_b32_e32 v15, 0xffff0000, v228
	v_lshlrev_b32_e32 v16, 16, v229
	v_and_b32_e32 v17, 0xffff0000, v229
	v_pk_mul_f32 v[26:27], v[14:15], v[48:49]
	v_pk_mul_f32 v[28:29], v[14:15], v[52:53]
	v_pk_mul_f32 v[30:31], v[14:15], v[56:57]
	v_pk_mul_f32 v[32:33], v[14:15], v[60:61]
	v_pk_mul_f32 v[34:35], v[14:15], v[64:65]
	v_pk_mul_f32 v[36:37], v[14:15], v[68:69]
	v_pk_mul_f32 v[38:39], v[14:15], v[72:73]
	v_pk_mul_f32 v[40:41], v[14:15], v[76:77]
	v_pk_fma_f32 v[26:27], v[16:17], v[50:51], v[26:27]
	v_pk_fma_f32 v[28:29], v[16:17], v[54:55], v[28:29]
	v_pk_fma_f32 v[30:31], v[16:17], v[58:59], v[30:31]
	v_pk_fma_f32 v[32:33], v[16:17], v[62:63], v[32:33]
	v_pk_fma_f32 v[34:35], v[16:17], v[66:67], v[34:35]
	v_pk_fma_f32 v[36:37], v[16:17], v[70:71], v[36:37]
	v_pk_fma_f32 v[38:39], v[16:17], v[74:75], v[38:39]
	v_pk_fma_f32 v[40:41], v[16:17], v[78:79], v[40:41]
	s_waitcnt vmcnt(12)
; #define LAS __attribute__((address_space(3)))
; DI float bflo(unsigned u) { return __uint_as_float(u << 16); }
; DI float bfhi(unsigned u) { return __uint_as_float(u & 0xffff0000u); }
; DI float rs_from_ss(u64 ssq) { return rsqrtf((float)ssq * (1.f / (1048576.f * 1024.f)) + EPS); }
; DI void phase_m_gates(int wv, const ArgP a, LAS unsigned char* lds) {
;     ...
;             for (int jj = 0; jj < 4; ++jj) { const int k0 = jj * 256 + lane * 4; const u32x2 hb = *(const u32x2*)(XBr + (size_t)t * 1024 + k0); const f32x4 hv = {bflo(hb.x), bfhi(hb.x), bflo(hb.y), bfhi(hb.y)};
; #pragma unroll
;                 for (int j = 0; j < 8; ++j) { const f32x4 wj = *(const LAS f32x4*)(wgs + j * 1024 + k0); acc[j] += hv[0] * wj[0] + hv[1] * wj[1] + hv[2] * wj[2] + hv[3] * wj[3]; } }
;             const float rs = rs_from_ss(rowss[t]);
;             { const bool b5 = lane & 32, b4 = lane & 16, b3 = lane & 8;
; #pragma unroll
;               for (int j = 0; j < 4; ++j) { const float snd = b5 ? acc[j] : acc[j + 4], kp = b5 ? acc[j + 4] : acc[j]; acc[j] = kp + __shfl_xor(snd, 32); }
; #pragma unroll
;               for (int j = 0; j < 2; ++j) { const float snd = b4 ? acc[j] : acc[j + 2], kp = b4 ? acc[j + 2] : acc[j]; acc[j] = kp + __shfl_xor(snd, 16); }
;               { const float snd = b3 ? acc[0] : acc[1], kp = b3 ? acc[1] : acc[0]; acc[0] = kp + __shfl_xor(snd, 8); }
;               acc[0] += __shfl_xor(acc[0], 4); acc[0] += __shfl_xor(acc[0], 2); acc[0] += __shfl_xor(acc[0], 1);
;               if ((lane & 7) == 0) pre[(wave * 8 + i) * 8 + (b5 ? 4 : 0) + (b4 ? 2 : 0) + (b3 ? 1 : 0)] = acc[0] * rs; }
	v_lshlrev_b32_e32 v18, 16, v230
	v_and_b32_e32 v19, 0xffff0000, v230
	v_lshlrev_b32_e32 v136, 16, v231
	v_and_b32_e32 v137, 0xffff0000, v231
	v_pk_fma_f32 v[26:27], v[18:19], v[80:81], v[26:27]
	v_pk_fma_f32 v[28:29], v[18:19], v[84:85], v[28:29]
	v_pk_fma_f32 v[30:31], v[18:19], v[88:89], v[30:31]
	v_pk_fma_f32 v[32:33], v[18:19], v[92:93], v[32:33]
	v_pk_fma_f32 v[34:35], v[18:19], v[96:97], v[34:35]
	v_pk_fma_f32 v[36:37], v[18:19], v[100:101], v[36:37]
	v_pk_fma_f32 v[38:39], v[18:19], v[104:105], v[38:39]
	v_pk_fma_f32 v[40:41], v[18:19], v[108:109], v[40:41]
	v_pk_fma_f32 v[26:27], v[136:137], v[82:83], v[26:27]
	v_pk_fma_f32 v[28:29], v[136:137], v[86:87], v[28:29]
	v_pk_fma_f32 v[30:31], v[136:137], v[90:91], v[30:31]
	v_pk_fma_f32 v[32:33], v[136:137], v[94:95], v[32:33]
	v_pk_fma_f32 v[34:35], v[136:137], v[98:99], v[34:35]
	v_pk_fma_f32 v[36:37], v[136:137], v[102:103], v[36:37]
	v_pk_fma_f32 v[38:39], v[136:137], v[106:107], v[38:39]
	v_pk_fma_f32 v[40:41], v[136:137], v[110:111], v[40:41]
	s_waitcnt vmcnt(11)
	v_lshlrev_b32_e32 v14, 16, v232
	v_and_b32_e32 v15, 0xffff0000, v232
	v_lshlrev_b32_e32 v16, 16, v233
	v_and_b32_e32 v17, 0xffff0000, v233
	v_pk_fma_f32 v[26:27], v[14:15], v[112:113], v[26:27]
	v_pk_fma_f32 v[28:29], v[14:15], v[116:117], v[28:29]
	v_pk_fma_f32 v[30:31], v[14:15], v[120:121], v[30:31]
	v_pk_fma_f32 v[32:33], v[14:15], v[124:125], v[32:33]
	v_pk_fma_f32 v[34:35], v[14:15], v[128:129], v[34:35]
	v_pk_fma_f32 v[36:37], v[14:15], v[132:133], v[36:37]
	v_pk_fma_f32 v[38:39], v[14:15], v[140:141], v[38:39]
	v_pk_fma_f32 v[40:41], v[14:15], v[144:145], v[40:41]
	v_pk_fma_f32 v[26:27], v[16:17], v[114:115], v[26:27]
	v_pk_fma_f32 v[28:29], v[16:17], v[118:119], v[28:29]
	v_pk_fma_f32 v[30:31], v[16:17], v[122:123], v[30:31]
	v_pk_fma_f32 v[32:33], v[16:17], v[126:127], v[32:33]
	v_pk_fma_f32 v[34:35], v[16:17], v[130:131], v[34:35]
	v_pk_fma_f32 v[36:37], v[16:17], v[134:135], v[36:37]
	v_pk_fma_f32 v[38:39], v[16:17], v[142:143], v[38:39]
	v_pk_fma_f32 v[40:41], v[16:17], v[146:147], v[40:41]
	s_waitcnt vmcnt(10)
	v_lshlrev_b32_e32 v18, 16, v234
	v_and_b32_e32 v19, 0xffff0000, v234
	v_lshlrev_b32_e32 v136, 16, v235
	v_and_b32_e32 v137, 0xffff0000, v235
	v_pk_fma_f32 v[26:27], v[18:19], v[148:149], v[26:27]
	v_pk_fma_f32 v[28:29], v[18:19], v[152:153], v[28:29]
	v_pk_fma_f32 v[30:31], v[18:19], v[156:157], v[30:31]
	v_pk_fma_f32 v[32:33], v[18:19], v[160:161], v[32:33]
	v_pk_fma_f32 v[34:35], v[18:19], v[164:165], v[34:35]
	v_pk_fma_f32 v[36:37], v[18:19], v[168:169], v[36:37]
	v_pk_fma_f32 v[38:39], v[18:19], v[172:173], v[38:39]
	v_pk_fma_f32 v[40:41], v[18:19], v[176:177], v[40:41]
	v_pk_fma_f32 v[26:27], v[136:137], v[150:151], v[26:27]
	v_pk_fma_f32 v[28:29], v[136:137], v[154:155], v[28:29]
	v_pk_fma_f32 v[30:31], v[136:137], v[158:159], v[30:31]
	v_pk_fma_f32 v[32:33], v[136:137], v[162:163], v[32:33]
	v_pk_fma_f32 v[34:35], v[136:137], v[166:167], v[34:35]
	v_pk_fma_f32 v[36:37], v[136:137], v[170:171], v[36:37]
	v_pk_fma_f32 v[38:39], v[136:137], v[174:175], v[38:39]
	v_pk_fma_f32 v[40:41], v[136:137], v[178:179], v[40:41]
	v_add_f32_e32 v26, v26, v27
	v_add_f32_e32 v28, v28, v29
	v_add_f32_e32 v30, v30, v31
	v_add_f32_e32 v32, v32, v33
	v_add_f32_e32 v34, v34, v35
	v_add_f32_e32 v36, v36, v37
	v_add_f32_e32 v38, v38, v39
	v_add_f32_e32 v40, v40, v41
	s_nop 1
	v_permlane32_swap_b32_e32 v26, v34
	v_permlane32_swap_b32_e32 v28, v36
	v_permlane32_swap_b32_e32 v30, v38
	v_permlane32_swap_b32_e32 v32, v40
	v_add_f32_e32 v26, v26, v34
	v_add_f32_e32 v30, v30, v38
	v_add_f32_e32 v28, v28, v36
	v_add_f32_e32 v32, v32, v40
	s_nop 1
	v_permlane16_swap_b32_e32 v26, v30
	v_permlane16_swap_b32_e32 v28, v32
	v_add_f32_e32 v26, v26, v30
	v_add_f32_e32 v28, v28, v32
	v_cndmask_b32_e64 v30, v26, v28, s[8:9]
	v_cndmask_b32_e64 v32, v28, v26, s[8:9]
	s_nop 1
	v_add_f32_dpp v26, v30, v32 row_ror:8 row_mask:0xf bank_mask:0xf
	s_nop 1
	v_add_f32_dpp v26, v26, v26 quad_perm:[1,0,3,2] row_mask:0xf bank_mask:0xf
	s_nop 1
	v_add_f32_dpp v26, v26, v26 quad_perm:[2,3,0,1] row_mask:0xf bank_mask:0xf
	s_nop 1
	v_add_f32_dpp v26, v26, v26 row_half_mirror row_mask:0xf bank_mask:0xf
	v_mul_f32_e32 v228, s69, v26
	s_waitcnt vmcnt(9)
	v_lshlrev_b32_e32 v14, 16, v236
	v_and_b32_e32 v15, 0xffff0000, v236
	v_lshlrev_b32_e32 v16, 16, v237
	v_and_b32_e32 v17, 0xffff0000, v237
	v_pk_mul_f32 v[26:27], v[14:15], v[48:49]
	v_pk_mul_f32 v[28:29], v[14:15], v[52:53]
	v_pk_mul_f32 v[30:31], v[14:15], v[56:57]
	v_pk_mul_f32 v[32:33], v[14:15], v[60:61]
	v_pk_mul_f32 v[34:35], v[14:15], v[64:65]
	v_pk_mul_f32 v[36:37], v[14:15], v[68:69]
	v_pk_mul_f32 v[38:39], v[14:15], v[72:73]
	v_pk_mul_f32 v[40:41], v[14:15], v[76:77]
	v_pk_fma_f32 v[26:27], v[16:17], v[50:51], v[26:27]
	v_pk_fma_f32 v[28:29], v[16:17], v[54:55], v[28:29]
	v_pk_fma_f32 v[30:31], v[16:17], v[58:59], v[30:31]
	v_pk_fma_f32 v[32:33], v[16:17], v[62:63], v[32:33]
	v_pk_fma_f32 v[34:35], v[16:17], v[66:67], v[34:35]
	v_pk_fma_f32 v[36:37], v[16:17], v[70:71], v[36:37]
	v_pk_fma_f32 v[38:39], v[16:17], v[74:75], v[38:39]
	v_pk_fma_f32 v[40:41], v[16:17], v[78:79], v[40:41]
	s_waitcnt vmcnt(8)
; #define LAS __attribute__((address_space(3)))
; DI float bflo(unsigned u) { return __uint_as_float(u << 16); }
; DI float bfhi(unsigned u) { return __uint_as_float(u & 0xffff0000u); }
; DI float rs_from_ss(u64 ssq) { return rsqrtf((float)ssq * (1.f / (1048576.f * 1024.f)) + EPS); }
; DI void phase_m_gates(int wv, const ArgP a, LAS unsigned char* lds) {
;     ...
;             for (int jj = 0; jj < 4; ++jj) { const int k0 = jj * 256 + lane * 4; const u32x2 hb = *(const u32x2*)(XBr + (size_t)t * 1024 + k0); const f32x4 hv = {bflo(hb.x), bfhi(hb.x), bflo(hb.y), bfhi(hb.y)};
; #pragma unroll
;                 for (int j = 0; j < 8; ++j) { const f32x4 wj = *(const LAS f32x4*)(wgs + j * 1024 + k0); acc[j] += hv[0] * wj[0] + hv[1] * wj[1] + hv[2] * wj[2] + hv[3] * wj[3]; } }
;             const float rs = rs_from_ss(rowss[t]);
;             { const bool b5 = lane & 32, b4 = lane & 16, b3 = lane & 8;
; #pragma unroll
;               for (int j = 0; j < 4; ++j) { const float snd = b5 ? acc[j] : acc[j + 4], kp = b5 ? acc[j + 4] : acc[j]; acc[j] = kp + __shfl_xor(snd, 32); }
; #pragma unroll
;               for (int j = 0; j < 2; ++j) { const float snd = b4 ? acc[j] : acc[j + 2], kp = b4 ? acc[j + 2] : acc[j]; acc[j] = kp + __shfl_xor(snd, 16); }
;               { const float snd = b3 ? acc[0] : acc[1], kp = b3 ? acc[1] : acc[0]; acc[0] = kp + __shfl_xor(snd, 8); }
;               acc[0] += __shfl_xor(acc[0], 4); acc[0] += __shfl_xor(acc[0], 2); acc[0] += __shfl_xor(acc[0], 1);
;               if ((lane & 7) == 0) pre[(wave * 8 + i) * 8 + (b5 ? 4 : 0) + (b4 ? 2 : 0) + (b3 ? 1 : 0)] = acc[0] * rs; }
	v_lshlrev_b32_e32 v18, 16, v238
	v_and_b32_e32 v19, 0xffff0000, v238
	v_lshlrev_b32_e32 v136, 16, v239
	v_and_b32_e32 v137, 0xffff0000, v239
	v_pk_fma_f32 v[26:27], v[18:19], v[80:81], v[26:27]
	v_pk_fma_f32 v[28:29], v[18:19], v[84:85], v[28:29]
	v_pk_fma_f32 v[30:31], v[18:19], v[88:89], v[30:31]
	v_pk_fma_f32 v[32:33], v[18:19], v[92:93], v[32:33]
	v_pk_fma_f32 v[34:35], v[18:19], v[96:97], v[34:35]
	v_pk_fma_f32 v[36:37], v[18:19], v[100:101], v[36:37]
	v_pk_fma_f32 v[38:39], v[18:19], v[104:105], v[38:39]
	v_pk_fma_f32 v[40:41], v[18:19], v[108:109], v[40:41]
	v_pk_fma_f32 v[26:27], v[136:137], v[82:83], v[26:27]
	v_pk_fma_f32 v[28:29], v[136:137], v[86:87], v[28:29]
	v_pk_fma_f32 v[30:31], v[136:137], v[90:91], v[30:31]
	v_pk_fma_f32 v[32:33], v[136:137], v[94:95], v[32:33]
	v_pk_fma_f32 v[34:35], v[136:137], v[98:99], v[34:35]
	v_pk_fma_f32 v[36:37], v[136:137], v[102:103], v[36:37]
	v_pk_fma_f32 v[38:39], v[136:137], v[106:107], v[38:39]
	v_pk_fma_f32 v[40:41], v[136:137], v[110:111], v[40:41]
	s_waitcnt vmcnt(7)
	v_lshlrev_b32_e32 v14, 16, v244
	v_and_b32_e32 v15, 0xffff0000, v244
	v_lshlrev_b32_e32 v16, 16, v245
	v_and_b32_e32 v17, 0xffff0000, v245
	v_pk_fma_f32 v[26:27], v[14:15], v[112:113], v[26:27]
	v_pk_fma_f32 v[28:29], v[14:15], v[116:117], v[28:29]
	v_pk_fma_f32 v[30:31], v[14:15], v[120:121], v[30:31]
	v_pk_fma_f32 v[32:33], v[14:15], v[124:125], v[32:33]
	v_pk_fma_f32 v[34:35], v[14:15], v[128:129], v[34:35]
	v_pk_fma_f32 v[36:37], v[14:15], v[132:133], v[36:37]
	v_pk_fma_f32 v[38:39], v[14:15], v[140:141], v[38:39]
	v_pk_fma_f32 v[40:41], v[14:15], v[144:145], v[40:41]
	v_pk_fma_f32 v[26:27], v[16:17], v[114:115], v[26:27]
	v_pk_fma_f32 v[28:29], v[16:17], v[118:119], v[28:29]
	v_pk_fma_f32 v[30:31], v[16:17], v[122:123], v[30:31]
	v_pk_fma_f32 v[32:33], v[16:17], v[126:127], v[32:33]
	v_pk_fma_f32 v[34:35], v[16:17], v[130:131], v[34:35]
	v_pk_fma_f32 v[36:37], v[16:17], v[134:135], v[36:37]
	v_pk_fma_f32 v[38:39], v[16:17], v[142:143], v[38:39]
	v_pk_fma_f32 v[40:41], v[16:17], v[146:147], v[40:41]
	s_waitcnt vmcnt(6)
	v_lshlrev_b32_e32 v18, 16, v246
	v_and_b32_e32 v19, 0xffff0000, v246
	v_lshlrev_b32_e32 v136, 16, v247
	v_and_b32_e32 v137, 0xffff0000, v247
	v_pk_fma_f32 v[26:27], v[18:19], v[148:149], v[26:27]
	v_pk_fma_f32 v[28:29], v[18:19], v[152:153], v[28:29]
	v_pk_fma_f32 v[30:31], v[18:19], v[156:157], v[30:31]
	v_pk_fma_f32 v[32:33], v[18:19], v[160:161], v[32:33]
	v_pk_fma_f32 v[34:35], v[18:19], v[164:165], v[34:35]
	v_pk_fma_f32 v[36:37], v[18:19], v[168:169], v[36:37]
	v_pk_fma_f32 v[38:39], v[18:19], v[172:173], v[38:39]
	v_pk_fma_f32 v[40:41], v[18:19], v[176:177], v[40:41]
	v_pk_fma_f32 v[26:27], v[136:137], v[150:151], v[26:27]
	v_pk_fma_f32 v[28:29], v[136:137], v[154:155], v[28:29]
	v_pk_fma_f32 v[30:31], v[136:137], v[158:159], v[30:31]
	v_pk_fma_f32 v[32:33], v[136:137], v[162:163], v[32:33]
	v_pk_fma_f32 v[34:35], v[136:137], v[166:167], v[34:35]
	v_pk_fma_f32 v[36:37], v[136:137], v[170:171], v[36:37]
	v_pk_fma_f32 v[38:39], v[136:137], v[174:175], v[38:39]
	v_pk_fma_f32 v[40:41], v[136:137], v[178:179], v[40:41]
	v_add_f32_e32 v26, v26, v27
	v_add_f32_e32 v28, v28, v29
	v_add_f32_e32 v30, v30, v31
	v_add_f32_e32 v32, v32, v33
	v_add_f32_e32 v34, v34, v35
	v_add_f32_e32 v36, v36, v37
	v_add_f32_e32 v38, v38, v39
	v_add_f32_e32 v40, v40, v41
	s_nop 1
	v_permlane32_swap_b32_e32 v26, v34
	v_permlane32_swap_b32_e32 v28, v36
	v_permlane32_swap_b32_e32 v30, v38
	v_permlane32_swap_b32_e32 v32, v40
	v_add_f32_e32 v26, v26, v34
	v_add_f32_e32 v30, v30, v38
	v_add_f32_e32 v28, v28, v36
	v_add_f32_e32 v32, v32, v40
	s_nop 1
	v_permlane16_swap_b32_e32 v26, v30
	v_permlane16_swap_b32_e32 v28, v32
	v_add_f32_e32 v26, v26, v30
	v_add_f32_e32 v28, v28, v32
	v_cndmask_b32_e64 v30, v26, v28, s[8:9]
	v_cndmask_b32_e64 v32, v28, v26, s[8:9]
	s_nop 1
	v_add_f32_dpp v26, v30, v32 row_ror:8 row_mask:0xf bank_mask:0xf
	s_nop 1
	v_add_f32_dpp v26, v26, v26 quad_perm:[1,0,3,2] row_mask:0xf bank_mask:0xf
	s_nop 1
	v_add_f32_dpp v26, v26, v26 quad_perm:[2,3,0,1] row_mask:0xf bank_mask:0xf
	s_nop 1
	v_add_f32_dpp v26, v26, v26 row_half_mirror row_mask:0xf bank_mask:0xf
	v_mul_f32_e32 v236, s70, v26
	s_waitcnt vmcnt(5)
	v_lshlrev_b32_e32 v14, 16, v248
	v_and_b32_e32 v15, 0xffff0000, v248
	v_lshlrev_b32_e32 v16, 16, v249
	v_and_b32_e32 v17, 0xffff0000, v249
	v_pk_mul_f32 v[26:27], v[14:15], v[48:49]
	v_pk_mul_f32 v[28:29], v[14:15], v[52:53]
	v_pk_mul_f32 v[30:31], v[14:15], v[56:57]
	v_pk_mul_f32 v[32:33], v[14:15], v[60:61]
	v_pk_mul_f32 v[34:35], v[14:15], v[64:65]
	v_pk_mul_f32 v[36:37], v[14:15], v[68:69]
	v_pk_mul_f32 v[38:39], v[14:15], v[72:73]
	v_pk_mul_f32 v[40:41], v[14:15], v[76:77]
	v_pk_fma_f32 v[26:27], v[16:17], v[50:51], v[26:27]
	v_pk_fma_f32 v[28:29], v[16:17], v[54:55], v[28:29]
	v_pk_fma_f32 v[30:31], v[16:17], v[58:59], v[30:31]
	v_pk_fma_f32 v[32:33], v[16:17], v[62:63], v[32:33]
	v_pk_fma_f32 v[34:35], v[16:17], v[66:67], v[34:35]
	v_pk_fma_f32 v[36:37], v[16:17], v[70:71], v[36:37]
	v_pk_fma_f32 v[38:39], v[16:17], v[74:75], v[38:39]
	v_pk_fma_f32 v[40:41], v[16:17], v[78:79], v[40:41]
	s_waitcnt vmcnt(4)
; DI void phase_m_gates(int wv, const ArgP a, LAS unsigned char* lds) {
;     ...
;             { const bool b5 = lane & 32, b4 = lane & 16, b3 = lane & 8;
; #pragma unroll
;               for (int j = 0; j < 4; ++j) { const float snd = b5 ? acc[j] : acc[j + 4], kp = b5 ? acc[j + 4] : acc[j]; acc[j] = kp + __shfl_xor(snd, 32); }
; #pragma unroll
;               for (int j = 0; j < 2; ++j) { const float snd = b4 ? acc[j] : acc[j + 2], kp = b4 ? acc[j + 2] : acc[j]; acc[j] = kp + __shfl_xor(snd, 16); }
;               { const float snd = b3 ? acc[0] : acc[1], kp = b3 ? acc[1] : acc[0]; acc[0] = kp + __shfl_xor(snd, 8); }
;               acc[0] += __shfl_xor(acc[0], 4); acc[0] += __shfl_xor(acc[0], 2); acc[0] += __shfl_xor(acc[0], 1);
;               if ((lane & 7) == 0) pre[(wave * 8 + i) * 8 + (b5 ? 4 : 0) + (b4 ? 2 : 0) + (b3 ? 1 : 0)] = acc[0] * rs; }
;         }
;         __syncthreads();
;         if (wave < 4) { const int h = wave; const float bi = a.in(18)[h], bfg = a.in(19)[h];
;             const float ig = 15.f * tanhf((pre[lane * 8 + h] + bi) * (1.f / 15.f));
;             const float fg = 15.f * tanhf((pre[lane * 8 + 4 + h] + bfg) * (1.f / 15.f));
	v_lshlrev_b32_e32 v18, 16, v250
	v_and_b32_e32 v19, 0xffff0000, v250
	v_lshlrev_b32_e32 v136, 16, v251
	v_and_b32_e32 v137, 0xffff0000, v251
	v_pk_fma_f32 v[26:27], v[18:19], v[80:81], v[26:27]
	v_pk_fma_f32 v[28:29], v[18:19], v[84:85], v[28:29]
	v_pk_fma_f32 v[30:31], v[18:19], v[88:89], v[30:31]
	v_pk_fma_f32 v[32:33], v[18:19], v[92:93], v[32:33]
	v_pk_fma_f32 v[34:35], v[18:19], v[96:97], v[34:35]
	v_pk_fma_f32 v[36:37], v[18:19], v[100:101], v[36:37]
	v_pk_fma_f32 v[38:39], v[18:19], v[104:105], v[38:39]
	v_pk_fma_f32 v[40:41], v[18:19], v[108:109], v[40:41]
	v_pk_fma_f32 v[26:27], v[136:137], v[82:83], v[26:27]
	v_pk_fma_f32 v[28:29], v[136:137], v[86:87], v[28:29]
	v_pk_fma_f32 v[30:31], v[136:137], v[90:91], v[30:31]
	v_pk_fma_f32 v[32:33], v[136:137], v[94:95], v[32:33]
	v_pk_fma_f32 v[34:35], v[136:137], v[98:99], v[34:35]
	v_pk_fma_f32 v[36:37], v[136:137], v[102:103], v[36:37]
	v_pk_fma_f32 v[38:39], v[136:137], v[106:107], v[38:39]
	v_pk_fma_f32 v[40:41], v[136:137], v[110:111], v[40:41]
	s_waitcnt vmcnt(3)
	v_lshlrev_b32_e32 v14, 16, v252
	v_and_b32_e32 v15, 0xffff0000, v252
	v_lshlrev_b32_e32 v16, 16, v253
	v_and_b32_e32 v17, 0xffff0000, v253
	v_pk_fma_f32 v[26:27], v[14:15], v[112:113], v[26:27]
	v_pk_fma_f32 v[28:29], v[14:15], v[116:117], v[28:29]
	v_pk_fma_f32 v[30:31], v[14:15], v[120:121], v[30:31]
	v_pk_fma_f32 v[32:33], v[14:15], v[124:125], v[32:33]
	v_pk_fma_f32 v[34:35], v[14:15], v[128:129], v[34:35]
	v_pk_fma_f32 v[36:37], v[14:15], v[132:133], v[36:37]
	v_pk_fma_f32 v[38:39], v[14:15], v[140:141], v[38:39]
	v_pk_fma_f32 v[40:41], v[14:15], v[144:145], v[40:41]
	v_pk_fma_f32 v[26:27], v[16:17], v[114:115], v[26:27]
	v_pk_fma_f32 v[28:29], v[16:17], v[118:119], v[28:29]
	v_pk_fma_f32 v[30:31], v[16:17], v[122:123], v[30:31]
	v_pk_fma_f32 v[32:33], v[16:17], v[126:127], v[32:33]
	v_pk_fma_f32 v[34:35], v[16:17], v[130:131], v[34:35]
	v_pk_fma_f32 v[36:37], v[16:17], v[134:135], v[36:37]
	v_pk_fma_f32 v[38:39], v[16:17], v[142:143], v[38:39]
	v_pk_fma_f32 v[40:41], v[16:17], v[146:147], v[40:41]
	s_waitcnt vmcnt(2)
	v_lshlrev_b32_e32 v18, 16, v254
	v_and_b32_e32 v19, 0xffff0000, v254
	v_lshlrev_b32_e32 v136, 16, v255
	v_and_b32_e32 v137, 0xffff0000, v255
	v_pk_fma_f32 v[26:27], v[18:19], v[148:149], v[26:27]
	v_pk_fma_f32 v[28:29], v[18:19], v[152:153], v[28:29]
	v_pk_fma_f32 v[30:31], v[18:19], v[156:157], v[30:31]
	v_pk_fma_f32 v[32:33], v[18:19], v[160:161], v[32:33]
	v_pk_fma_f32 v[34:35], v[18:19], v[164:165], v[34:35]
	v_pk_fma_f32 v[36:37], v[18:19], v[168:169], v[36:37]
	v_pk_fma_f32 v[38:39], v[18:19], v[172:173], v[38:39]
	v_pk_fma_f32 v[40:41], v[18:19], v[176:177], v[40:41]
	v_pk_fma_f32 v[26:27], v[136:137], v[150:151], v[26:27]
	v_pk_fma_f32 v[28:29], v[136:137], v[154:155], v[28:29]
	v_pk_fma_f32 v[30:31], v[136:137], v[158:159], v[30:31]
	v_pk_fma_f32 v[32:33], v[136:137], v[162:163], v[32:33]
	v_pk_fma_f32 v[34:35], v[136:137], v[166:167], v[34:35]
	v_pk_fma_f32 v[36:37], v[136:137], v[170:171], v[36:37]
	v_pk_fma_f32 v[38:39], v[136:137], v[174:175], v[38:39]
	v_pk_fma_f32 v[40:41], v[136:137], v[178:179], v[40:41]
	v_add_f32_e32 v26, v26, v27
	v_add_f32_e32 v28, v28, v29
	v_add_f32_e32 v30, v30, v31
	v_add_f32_e32 v32, v32, v33
	v_add_f32_e32 v34, v34, v35
	v_add_f32_e32 v36, v36, v37
	v_add_f32_e32 v38, v38, v39
	v_add_f32_e32 v40, v40, v41
	s_nop 1
	v_permlane32_swap_b32_e32 v26, v34
	v_permlane32_swap_b32_e32 v28, v36
	v_permlane32_swap_b32_e32 v30, v38
	v_permlane32_swap_b32_e32 v32, v40
	v_add_f32_e32 v26, v26, v34
	v_add_f32_e32 v30, v30, v38
	v_add_f32_e32 v28, v28, v36
	v_add_f32_e32 v32, v32, v40
	s_nop 1
	v_permlane16_swap_b32_e32 v26, v30
	v_permlane16_swap_b32_e32 v28, v32
	v_add_f32_e32 v26, v26, v30
	v_add_f32_e32 v28, v28, v32
	v_cndmask_b32_e64 v30, v26, v28, s[8:9]
	v_cndmask_b32_e64 v32, v28, v26, s[8:9]
	s_nop 1
	v_add_f32_dpp v26, v30, v32 row_ror:8 row_mask:0xf bank_mask:0xf
	s_nop 1
	v_add_f32_dpp v26, v26, v26 quad_perm:[1,0,3,2] row_mask:0xf bank_mask:0xf
	s_nop 1
	v_add_f32_dpp v26, v26, v26 quad_perm:[2,3,0,1] row_mask:0xf bank_mask:0xf
	s_nop 1
	v_add_f32_dpp v26, v26, v26 row_half_mirror row_mask:0xf bank_mask:0xf
	v_mul_f32_e32 v248, s71, v26
	v_mov_b32_e32 v9, v5
	s_and_saveexec_b64 s[44:45], s[10:11]
	ds_write_b32 v9, v180
	ds_write_b32 v9, v188 offset:32
	ds_write_b32 v9, v204 offset:64
	ds_write_b32 v9, v212 offset:96
	ds_write_b32 v9, v220 offset:128
	ds_write_b32 v9, v228 offset:160
	ds_write_b32 v9, v236 offset:192
	ds_write_b32 v9, v248 offset:224
	s_or_b64 exec, exec, s[44:45]
.LBB0_1395:
	s_waitcnt lgkmcnt(0)
	s_barrier
	s_and_saveexec_b64 s[44:45], s[12:13]
	s_cbranch_execz .LBB0_1384
	ds_read_b32 v14, v20 offset:32768
	s_waitcnt vmcnt(0)
	v_mov_b32_e32 v9, v196
	v_mov_b32_e32 v15, v241
	s_waitcnt lgkmcnt(0)
	v_add_f32_e32 v9, v9, v14
	v_mul_f32_e32 v9, 0x3d888889, v9
	v_cmp_nlt_f32_e64 s[46:47], |v9|, s50
	s_and_saveexec_b64 s[62:63], s[46:47]
	s_xor_b64 s[46:47], exec, s[62:63]
	s_cbranch_execz .LBB0_1398
	v_add_f32_e64 v14, |v9|, |v9|
	v_mul_f32_e32 v16, 0x3fb8aa3b, v14
	v_rndne_f32_e32 v17, v16
	v_sub_f32_e32 v18, v16, v17
	v_fma_f32 v16, v14, s51, -v16
	v_fmac_f32_e32 v16, 0x32a5705f, v14
	v_add_f32_e32 v16, v18, v16
	v_cvt_i32_f32_e32 v17, v17
	v_exp_f32_e32 v16, v16
	v_cmp_ngt_f32_e32 vcc, s52, v14
	v_ldexp_f32 v16, v16, v17
	s_nop 0
	v_cndmask_b32_e32 v16, 0, v16, vcc
	v_cmp_nlt_f32_e32 vcc, s53, v14
	s_nop 1
	v_cndmask_b32_e32 v14, v24, v16, vcc
	v_add_f32_e32 v14, 1.0, v14
	v_rcp_f32_e32 v14, v14
	s_nop 0
	v_fma_f32 v14, v14, -2.0, 1.0
